# cross_unit K-step fragment reads software-pipelined over 4 quads with exact vmcnt (both instantiations) + small_gemm compute chunks (P1/P7/P8 loops): every ds_read_b128 gets a fresh fragment quad, iss
# speedup vs baseline: 1.0069x; 1.0069x over previous
.LBB0_456:
	s_cmp_gt_u32 s7, 12
	ds_read_b128 v[102:105], v78 offset:18432
	ds_read_b128 v[106:109], v80
	ds_read_b128 v[110:113], v78 offset:20736
	ds_read_b128 v[114:117], v78 offset:23040
	ds_read_b128 v[118:121], v78 offset:25344
	ds_read_b128 v[122:125], v78 offset:29952
	ds_read_b128 v[126:129], v78 offset:34560
	s_waitcnt lgkmcnt(5)
	v_mfma_f32_16x16x32_bf16 v[64:67], v[102:105], v[106:109], v[64:67]
	ds_read_b128 v[102:105], v78 offset:27648
	s_waitcnt lgkmcnt(5)
	v_mfma_f32_16x16x32_bf16 v[28:31], v[110:113], v[106:109], v[28:31]
	ds_read_b128 v[110:113], v78 offset:32256
	ds_read_b128 v[130:133], v78 offset:18496
	s_waitcnt lgkmcnt(5)
	v_mfma_f32_16x16x32_bf16 v[20:23], v[118:121], v[106:109], v[20:23]
	ds_read_b128 v[98:101], v80 offset:64
	s_waitcnt lgkmcnt(5)
	v_mfma_f32_16x16x32_bf16 v[90:93], v[122:125], v[106:109], v[12:15]
	s_waitcnt lgkmcnt(7)
	v_mfma_f32_16x16x32_bf16 v[24:27], v[114:117], v[106:109], v[24:27]
	ds_read_b128 v[114:117], v78 offset:23104
	ds_read_b128 v[118:121], v78 offset:20800
	s_waitcnt lgkmcnt(5)
	v_mfma_f32_16x16x32_bf16 v[82:85], v[102:105], v[106:109], v[16:19]
	ds_read_b128 v[102:105], v78 offset:25408
	s_waitcnt lgkmcnt(5)
	v_mfma_f32_16x16x32_bf16 v[94:97], v[110:113], v[106:109], v[8:11]
	s_waitcnt lgkmcnt(7)
	v_mfma_f32_16x16x32_bf16 v[4:7], v[126:129], v[106:109], v[4:7]
	ds_read_b128 v[106:109], v78 offset:27712
	s_waitcnt lgkmcnt(2)
	v_mfma_f32_16x16x32_bf16 v[12:15], v[118:121], v[98:101], v[28:31]
	s_nop 2
	ds_read_b128 v[28:31], v78 offset:30016
	s_waitcnt lgkmcnt(4)
	v_mfma_f32_16x16x32_bf16 v[16:19], v[114:117], v[98:101], v[24:27]
	s_waitcnt lgkmcnt(2)
	v_mfma_f32_16x16x32_bf16 v[20:23], v[102:105], v[98:101], v[20:23]
	s_waitcnt lgkmcnt(5)
	v_mfma_f32_16x16x32_bf16 v[8:11], v[130:133], v[98:101], v[64:67]
	s_waitcnt lgkmcnt(1)
	v_mfma_f32_16x16x32_bf16 v[24:27], v[106:109], v[98:101], v[82:85]
	s_waitcnt lgkmcnt(1)
	s_nop 0
	ds_read_b128 v[64:67], v78 offset:32320
	s_nop 0
	ds_read_b128 v[82:85], v78 offset:34624
	s_waitcnt vmcnt(3)
	ds_write_b128 v81, v[40:43] offset:36864
	s_waitcnt vmcnt(2)
	ds_write_b128 v81, v[44:47] offset:46080
	s_waitcnt vmcnt(1)
	ds_write_b128 v81, v[56:59] offset:55296
	s_waitcnt vmcnt(0)
	ds_write_b128 v81, v[60:63] offset:64512
	s_waitcnt lgkmcnt(6)
	v_mfma_f32_16x16x32_bf16 v[28:31], v[28:31], v[98:101], v[90:93]
	s_waitcnt lgkmcnt(0)
	s_barrier
	s_waitcnt lgkmcnt(5)
	v_mfma_f32_16x16x32_bf16 v[64:67], v[64:67], v[98:101], v[94:97]
	s_waitcnt lgkmcnt(4)
	v_mfma_f32_16x16x32_bf16 v[4:7], v[82:85], v[98:101], v[4:7]
	s_cbranch_scc1 .LBB0_458
	v_add_co_u32_e32 v40, vcc, 0x11400000, v76
	s_nop 1
	v_addc_co_u32_e32 v41, vcc, 0, v77, vcc
	v_add_co_u32_e32 v44, vcc, 0x11420000, v76
	s_nop 1
	v_addc_co_u32_e32 v45, vcc, 0, v77, vcc
	v_add_co_u32_e32 v56, vcc, 0x400000, v74
	global_load_dwordx4 v[40:43], v[40:41], off offset:384
	s_nop 0
	global_load_dwordx4 v[44:47], v[44:45], off offset:384
	v_addc_co_u32_e32 v57, vcc, 0, v75, vcc
	v_add_co_u32_e32 v60, vcc, 0x420000, v74
	s_nop 1
	v_addc_co_u32_e32 v61, vcc, 0, v75, vcc
	global_load_dwordx4 v[56:59], v[56:57], off offset:384
	s_nop 0
	global_load_dwordx4 v[60:63], v[60:61], off offset:384
.LBB0_458:
	s_andn2_b64 vcc, exec, s[4:5]
	ds_read_b128 v[98:101], v78 offset:55296
	ds_read_b128 v[102:105], v80 offset:36864
	ds_read_b128 v[106:109], v78 offset:57600
	ds_read_b128 v[110:113], v78 offset:59904
	ds_read_b128 v[114:117], v78 offset:62208
	ds_read_b128 v[118:121], v78 offset:64512
	ds_read_b128 v[122:125], v79 offset:11520
	s_waitcnt lgkmcnt(5)
	v_mfma_f32_16x16x32_bf16 v[8:11], v[98:101], v[102:105], v[8:11]
	ds_read_b128 v[98:101], v79 offset:13824
	s_waitcnt lgkmcnt(5)
	v_mfma_f32_16x16x32_bf16 v[12:15], v[106:109], v[102:105], v[12:15]
	ds_read_b128 v[106:109], v79 offset:16128
	s_waitcnt lgkmcnt(5)
	v_mfma_f32_16x16x32_bf16 v[16:19], v[110:113], v[102:105], v[16:19]
	ds_read_b128 v[110:113], v78 offset:55360
	s_waitcnt lgkmcnt(5)
	v_mfma_f32_16x16x32_bf16 v[20:23], v[114:117], v[102:105], v[20:23]
	ds_read_b128 v[114:117], v80 offset:36928
	s_waitcnt lgkmcnt(5)
	v_mfma_f32_16x16x32_bf16 v[74:77], v[118:121], v[102:105], v[24:27]
	ds_read_b128 v[118:121], v78 offset:57664
	s_waitcnt lgkmcnt(5)
	v_mfma_f32_16x16x32_bf16 v[86:89], v[122:125], v[102:105], v[28:31]
	ds_read_b128 v[122:125], v78 offset:59968
	s_waitcnt lgkmcnt(5)
	v_mfma_f32_16x16x32_bf16 v[90:93], v[98:101], v[102:105], v[64:67]
	ds_read_b128 v[98:101], v78 offset:62272
	s_waitcnt lgkmcnt(5)
	v_mfma_f32_16x16x32_bf16 v[4:7], v[106:109], v[102:105], v[4:7]
	ds_read_b128 v[102:105], v78 offset:64576
	ds_read_b128 v[106:109], v79 offset:11584
	s_waitcnt lgkmcnt(5)
	v_mfma_f32_16x16x32_bf16 v[64:67], v[110:113], v[114:117], v[8:11]
	ds_read_b128 v[110:113], v79 offset:13888
	s_waitcnt lgkmcnt(5)
	v_mfma_f32_16x16x32_bf16 v[28:31], v[118:121], v[114:117], v[12:15]
	ds_read_b128 v[118:121], v79 offset:16192
	s_waitcnt lgkmcnt(5)
	v_mfma_f32_16x16x32_bf16 v[24:27], v[122:125], v[114:117], v[16:19]
	s_waitcnt lgkmcnt(4)
	v_mfma_f32_16x16x32_bf16 v[20:23], v[98:101], v[114:117], v[20:23]
	s_waitcnt lgkmcnt(3)
	v_mfma_f32_16x16x32_bf16 v[16:19], v[102:105], v[114:117], v[74:77]
	s_waitcnt lgkmcnt(2)
	v_mfma_f32_16x16x32_bf16 v[12:15], v[106:109], v[114:117], v[86:89]
	s_waitcnt lgkmcnt(1)
	v_mfma_f32_16x16x32_bf16 v[8:11], v[110:113], v[114:117], v[90:93]
	s_waitcnt lgkmcnt(0)
	v_mfma_f32_16x16x32_bf16 v[4:7], v[118:121], v[114:117], v[4:7]
	s_waitcnt lgkmcnt(0)
	s_cbranch_vccnz .LBB0_453
	ds_write_b128 v81, v[32:35]
	ds_write_b128 v81, v[36:39] offset:9216
	ds_write_b128 v81, v[48:51] offset:18432
	ds_write_b128 v81, v[52:55] offset:27648
	s_branch .LBB0_453

.LBB0_904:
	s_cmp_gt_u32 s8, 12
	ds_read_b128 v[148:151], v80
	ds_read_b128 v[152:155], v78 offset:18432
	ds_read_b128 v[156:159], v78 offset:20736
	ds_read_b128 v[160:163], v78 offset:23040
	ds_read_b128 v[164:167], v78 offset:25344
	ds_read_b128 v[168:171], v78 offset:27648
	ds_read_b128 v[172:175], v78 offset:29952
	s_waitcnt lgkmcnt(5)
	v_mfma_f32_16x16x32_bf16 v[64:67], v[152:155], v[148:151], v[64:67]
	ds_read_b128 v[152:155], v78 offset:32256
	s_waitcnt lgkmcnt(5)
	v_mfma_f32_16x16x32_bf16 v[28:31], v[156:159], v[148:151], v[28:31]
	ds_read_b128 v[156:159], v78 offset:34560
	s_waitcnt lgkmcnt(5)
	v_mfma_f32_16x16x32_bf16 v[24:27], v[160:163], v[148:151], v[24:27]
	ds_read_b128 v[98:101], v80 offset:64
	s_waitcnt lgkmcnt(5)
	v_mfma_f32_16x16x32_bf16 v[20:23], v[164:167], v[148:151], v[20:23]
	ds_read_b128 v[160:163], v78 offset:18496
	s_waitcnt lgkmcnt(5)
	v_mfma_f32_16x16x32_bf16 v[86:89], v[168:171], v[148:151], v[16:19]
	ds_read_b128 v[164:167], v78 offset:20800
	s_waitcnt lgkmcnt(5)
	v_mfma_f32_16x16x32_bf16 v[90:93], v[172:175], v[148:151], v[12:15]
	ds_read_b128 v[168:171], v78 offset:23104
	s_waitcnt lgkmcnt(5)
	v_mfma_f32_16x16x32_bf16 v[94:97], v[152:155], v[148:151], v[8:11]
	ds_read_b128 v[152:155], v78 offset:25408
	s_waitcnt lgkmcnt(5)
	v_mfma_f32_16x16x32_bf16 v[82:85], v[156:159], v[148:151], v[4:7]
	s_waitcnt lgkmcnt(3)
	v_mfma_f32_16x16x32_bf16 v[4:7], v[160:163], v[98:101], v[64:67]
	s_nop 2
	ds_read_b128 v[64:67], v78 offset:34624
	s_waitcnt lgkmcnt(3)
	v_mfma_f32_16x16x32_bf16 v[8:11], v[164:167], v[98:101], v[28:31]
	s_nop 2
	ds_read_b128 v[28:31], v78 offset:32320
	s_waitcnt lgkmcnt(3)
	v_mfma_f32_16x16x32_bf16 v[12:15], v[168:171], v[98:101], v[24:27]
	s_nop 2
	ds_read_b128 v[24:27], v78 offset:30016
	ds_read_b128 v[148:151], v78 offset:27712
	s_waitcnt lgkmcnt(4)
	v_mfma_f32_16x16x32_bf16 v[16:19], v[152:155], v[98:101], v[20:23]
	s_waitcnt lgkmcnt(0)
	v_mfma_f32_16x16x32_bf16 v[20:23], v[148:151], v[98:101], v[86:89]
	s_waitcnt lgkmcnt(0)
	s_waitcnt vmcnt(3)
	ds_write_b128 v81, v[40:43] offset:36864
	s_waitcnt vmcnt(2)
	ds_write_b128 v81, v[44:47] offset:46080
	s_waitcnt vmcnt(1)
	ds_write_b128 v81, v[56:59] offset:55296
	s_waitcnt vmcnt(0)
	ds_write_b128 v81, v[60:63] offset:64512
	s_waitcnt lgkmcnt(0)
	s_barrier
	v_mfma_f32_16x16x32_bf16 v[24:27], v[24:27], v[98:101], v[90:93]
	v_mfma_f32_16x16x32_bf16 v[28:31], v[28:31], v[98:101], v[94:97]
	v_mfma_f32_16x16x32_bf16 v[64:67], v[64:67], v[98:101], v[82:85]
	s_cbranch_scc1 .LBB0_906
	v_add_co_u32_e32 v40, vcc, 0x11400000, v76
	s_nop 1
	v_addc_co_u32_e32 v41, vcc, 0, v77, vcc
	v_add_co_u32_e32 v44, vcc, 0x11420000, v76
	s_nop 1
	v_addc_co_u32_e32 v45, vcc, 0, v77, vcc
	v_add_co_u32_e32 v56, vcc, 0x400000, v74
	global_load_dwordx4 v[40:43], v[40:41], off offset:384
	s_nop 0
	global_load_dwordx4 v[44:47], v[44:45], off offset:384
	v_addc_co_u32_e32 v57, vcc, 0, v75, vcc
	v_add_co_u32_e32 v60, vcc, 0x420000, v74
	s_nop 1
	v_addc_co_u32_e32 v61, vcc, 0, v75, vcc
	global_load_dwordx4 v[56:59], v[56:57], off offset:384
	s_nop 0
	global_load_dwordx4 v[60:63], v[60:61], off offset:384
.LBB0_906:
	s_andn2_b64 vcc, exec, s[4:5]
	ds_read_b128 v[148:151], v80 offset:36864
	ds_read_b128 v[152:155], v78 offset:55296
	ds_read_b128 v[156:159], v78 offset:57600
	ds_read_b128 v[160:163], v78 offset:59904
	ds_read_b128 v[164:167], v78 offset:62208
	ds_read_b128 v[168:171], v78 offset:64512
	ds_read_b128 v[172:175], v79 offset:11520
	s_waitcnt lgkmcnt(5)
	v_mfma_f32_16x16x32_bf16 v[4:7], v[152:155], v[148:151], v[4:7]
	ds_read_b128 v[152:155], v79 offset:13824
	s_waitcnt lgkmcnt(5)
	v_mfma_f32_16x16x32_bf16 v[8:11], v[156:159], v[148:151], v[8:11]
	ds_read_b128 v[156:159], v79 offset:16128
	s_waitcnt lgkmcnt(5)
	v_mfma_f32_16x16x32_bf16 v[12:15], v[160:163], v[148:151], v[12:15]
	ds_read_b128 v[94:97], v80 offset:36928
	s_waitcnt lgkmcnt(5)
	v_mfma_f32_16x16x32_bf16 v[16:19], v[164:167], v[148:151], v[16:19]
	ds_read_b128 v[160:163], v78 offset:55360
	s_waitcnt lgkmcnt(5)
	v_mfma_f32_16x16x32_bf16 v[82:85], v[168:171], v[148:151], v[20:23]
	ds_read_b128 v[164:167], v78 offset:57664
	s_waitcnt lgkmcnt(5)
	v_mfma_f32_16x16x32_bf16 v[86:89], v[172:175], v[148:151], v[24:27]
	ds_read_b128 v[168:171], v78 offset:59968
	s_waitcnt lgkmcnt(5)
	v_mfma_f32_16x16x32_bf16 v[90:93], v[152:155], v[148:151], v[28:31]
	ds_read_b128 v[152:155], v78 offset:62272
	s_waitcnt lgkmcnt(5)
	v_mfma_f32_16x16x32_bf16 v[74:77], v[156:159], v[148:151], v[64:67]
	ds_read_b128 v[148:151], v78 offset:64576
	ds_read_b128 v[156:159], v79 offset:11584
	s_waitcnt lgkmcnt(5)
	v_mfma_f32_16x16x32_bf16 v[64:67], v[160:163], v[94:97], v[4:7]
	ds_read_b128 v[160:163], v79 offset:13888
	s_waitcnt lgkmcnt(5)
	v_mfma_f32_16x16x32_bf16 v[28:31], v[164:167], v[94:97], v[8:11]
	ds_read_b128 v[164:167], v79 offset:16192
	s_waitcnt lgkmcnt(5)
	v_mfma_f32_16x16x32_bf16 v[24:27], v[168:171], v[94:97], v[12:15]
	s_waitcnt lgkmcnt(4)
	v_mfma_f32_16x16x32_bf16 v[20:23], v[152:155], v[94:97], v[16:19]
	s_waitcnt lgkmcnt(3)
	v_mfma_f32_16x16x32_bf16 v[16:19], v[148:151], v[94:97], v[82:85]
	s_waitcnt lgkmcnt(2)
	v_mfma_f32_16x16x32_bf16 v[12:15], v[156:159], v[94:97], v[86:89]
	s_waitcnt lgkmcnt(1)
	v_mfma_f32_16x16x32_bf16 v[8:11], v[160:163], v[94:97], v[90:93]
	s_waitcnt lgkmcnt(0)
	v_mfma_f32_16x16x32_bf16 v[4:7], v[164:167], v[94:97], v[74:77]
	s_waitcnt lgkmcnt(0)
	s_cbranch_vccnz .LBB0_901
	ds_write_b128 v81, v[32:35]
	ds_write_b128 v81, v[36:39] offset:9216
	ds_write_b128 v81, v[48:51] offset:18432
	ds_write_b128 v81, v[52:55] offset:27648
	s_branch .LBB0_901

.LBB0_2276:
	s_lshl_b32 s27, s17, 2
	v_bfe_u32 v2, v118, 4, 2
	v_or_b32_e32 v4, s27, v2
	v_and_b32_e32 v5, 15, v118
	v_bitop3_b32 v4, v4, v5, 7 bitop3:0x6c
	v_lshlrev_b32_e32 v4, 4, v4
	s_lshl_b32 s4, s17, 13
	v_lshlrev_b32_e32 v2, 11, v2
	v_or3_b32 v2, s4, v2, v4
	s_add_u32 s4, s15, s2
	s_addc_u32 s5, s16, s3
	s_waitcnt lgkmcnt(0)
	v_lshl_add_u64 v[82:83], s[4:5], 0, v[2:3]
	s_mov_b64 s[4:5], 0x4400000
	v_lshl_add_u64 v[4:5], v[82:83], 0, s[4:5]
	s_lshl_b32 s4, s17, 10
	s_add_i32 s25, s4, 0
	s_mov_b32 m0, s25
	s_mov_b64 s[4:5], 0x4410000
	s_add_i32 s24, s25, 0x2000
	global_load_lds_dwordx4 v[4:5], off
	v_lshl_add_u64 v[4:5], v[82:83], 0, s[4:5]
	s_mov_b32 m0, s24
	s_mov_b64 s[4:5], 0x4400100
	s_add_i32 s23, s25, 0x4000
	global_load_lds_dwordx4 v[4:5], off
	v_lshl_add_u64 v[4:5], v[82:83], 0, s[4:5]
	s_mov_b32 m0, s23
	s_mov_b64 s[4:5], 0x4410100
	s_add_i32 s22, s25, 0x6000
	global_load_lds_dwordx4 v[4:5], off
	v_lshl_add_u64 v[4:5], v[82:83], 0, s[4:5]
	s_mov_b32 m0, s22
	s_mov_b64 s[4:5], 0x4420000
	s_add_i32 s21, s25, 0x8000
	global_load_lds_dwordx4 v[4:5], off
	v_lshl_add_u64 v[4:5], v[82:83], 0, s[4:5]
	s_mov_b32 m0, s21
	s_mov_b64 s[4:5], 0x4430000
	s_add_i32 s20, s25, 0xa000
	global_load_lds_dwordx4 v[4:5], off
	v_lshl_add_u64 v[4:5], v[82:83], 0, s[4:5]
	s_mov_b32 m0, s20
	s_mov_b64 s[4:5], 0x4420100
	global_load_lds_dwordx4 v[4:5], off
	s_waitcnt vmcnt(4)
	s_add_i32 s19, s25, 0xc000
	s_waitcnt lgkmcnt(0)
	s_barrier
	v_lshl_add_u64 v[4:5], v[82:83], 0, s[4:5]
	s_mov_b32 m0, s19
	s_mov_b64 s[4:5], 0x4430100
	s_add_i32 s18, s25, 0xe000
	global_load_lds_dwordx4 v[4:5], off
	v_lshl_add_u64 v[4:5], v[82:83], 0, s[4:5]
	s_mov_b32 m0, s18
	v_bfe_u32 v218, v118, 5, 1
	global_load_lds_dwordx4 v[4:5], off
	v_cndmask_b32_e64 v2, 0, 1, s[6:7]
	v_cmp_ne_u32_e64 s[4:5], 1, v2
	v_lshlrev_b32_e32 v231, 4, v218
	v_lshlrev_b32_e32 v2, 4, v1
	s_andn2_b64 vcc, exec, s[6:7]
	v_and_b32_e32 v222, 0x70, v2
	v_lshl_add_u32 v223, v1, 8, 0
	v_or_b32_e32 v230, 32, v231
	v_or_b32_e32 v229, 64, v231
	v_or_b32_e32 v228, 0x60, v231
	v_or_b32_e32 v227, 0x80, v231
	v_or_b32_e32 v226, 0xa0, v231
	v_or_b32_e32 v225, 0xc0, v231
	v_or_b32_e32 v224, 0xe0, v231
	s_cbranch_vccnz .LBB0_2278
	v_xad_u32 v60, v231, v222, v223
	ds_read_b128 v[8:11], v60
	ds_read_b128 v[12:15], v60 offset:8192
	v_xad_u32 v60, v230, v222, v223
	ds_read_b128 v[52:55], v60
	ds_read_b128 v[56:59], v60 offset:8192
	s_waitcnt vmcnt(8) lgkmcnt(3)
	v_mfma_f32_32x32x16_bf16 v[34:49], v[8:11], v[114:117], 0
	v_xad_u32 v60, v229, v222, v223
	ds_read_b128 v[8:11], v60
	s_waitcnt lgkmcnt(3)
	v_mfma_f32_32x32x16_bf16 v[18:33], v[12:15], v[114:117], 0
	ds_read_b128 v[12:15], v60 offset:8192
	s_waitcnt lgkmcnt(3)
	v_mfma_f32_32x32x16_bf16 v[34:49], v[52:55], v[202:205], v[34:49]
	v_xad_u32 v60, v228, v222, v223
	ds_read_b128 v[52:55], v60
	s_waitcnt lgkmcnt(3)
	v_mfma_f32_32x32x16_bf16 v[18:33], v[56:59], v[202:205], v[18:33]
	ds_read_b128 v[56:59], v60 offset:8192
	s_waitcnt lgkmcnt(3)
	v_mfma_f32_32x32x16_bf16 v[34:49], v[8:11], v[198:201], v[34:49]
	v_xad_u32 v60, v227, v222, v223
	ds_read_b128 v[8:11], v60
	s_waitcnt lgkmcnt(3)
	v_mfma_f32_32x32x16_bf16 v[18:33], v[12:15], v[198:201], v[18:33]
	ds_read_b128 v[12:15], v60 offset:8192
	s_waitcnt lgkmcnt(3)
	v_mfma_f32_32x32x16_bf16 v[34:49], v[52:55], v[194:197], v[34:49]
	v_xad_u32 v60, v226, v222, v223
	ds_read_b128 v[52:55], v60
	s_waitcnt lgkmcnt(3)
	v_mfma_f32_32x32x16_bf16 v[18:33], v[56:59], v[194:197], v[18:33]
	ds_read_b128 v[56:59], v60 offset:8192
	s_waitcnt lgkmcnt(3)
	v_mfma_f32_32x32x16_bf16 v[34:49], v[8:11], v[190:193], v[34:49]
	v_xad_u32 v60, v225, v222, v223
	ds_read_b128 v[8:11], v60
	s_waitcnt lgkmcnt(3)
	v_mfma_f32_32x32x16_bf16 v[18:33], v[12:15], v[190:193], v[18:33]
	ds_read_b128 v[12:15], v60 offset:8192
	s_waitcnt lgkmcnt(3)
	v_mfma_f32_32x32x16_bf16 v[34:49], v[52:55], v[186:189], v[34:49]
	v_xad_u32 v60, v224, v222, v223
	ds_read_b128 v[52:55], v60
	s_waitcnt lgkmcnt(3)
	v_mfma_f32_32x32x16_bf16 v[18:33], v[56:59], v[186:189], v[18:33]
	ds_read_b128 v[56:59], v60 offset:8192
	s_waitcnt lgkmcnt(3)
	v_mfma_f32_32x32x16_bf16 v[34:49], v[8:11], v[182:185], v[34:49]
	s_waitcnt lgkmcnt(2)
	v_mfma_f32_32x32x16_bf16 v[18:33], v[12:15], v[182:185], v[18:33]
	s_waitcnt lgkmcnt(1)
	v_mfma_f32_32x32x16_bf16 v[34:49], v[52:55], v[178:181], v[34:49]
	s_waitcnt lgkmcnt(0)
	v_mfma_f32_32x32x16_bf16 v[18:33], v[56:59], v[178:181], v[18:33]
	s_branch .LBB0_2279

.LBB0_2279:
	s_waitcnt vmcnt(4)
	s_mov_b64 s[6:7], 0x4440000
	s_mov_b32 m0, s25
	s_waitcnt lgkmcnt(0)
	s_barrier
	v_lshl_add_u64 v[4:5], v[82:83], 0, s[6:7]
	s_mov_b64 s[6:7], 0x4450000
	global_load_lds_dwordx4 v[4:5], off
	v_lshl_add_u64 v[4:5], v[82:83], 0, s[6:7]
	s_mov_b32 m0, s24
	s_and_b64 vcc, exec, s[4:5]
	global_load_lds_dwordx4 v[4:5], off
	s_cbranch_vccnz .LBB0_2281
	v_xad_u32 v60, v231, v222, v223
	ds_read_b128 v[8:11], v60 offset:16384
	ds_read_b128 v[12:15], v60 offset:24576
	v_xad_u32 v60, v230, v222, v223
	ds_read_b128 v[52:55], v60 offset:16384
	ds_read_b128 v[56:59], v60 offset:24576
	s_waitcnt lgkmcnt(3)
	v_mfma_f32_32x32x16_bf16 v[34:49], v[8:11], v[174:177], v[34:49]
	v_xad_u32 v60, v229, v222, v223
	ds_read_b128 v[8:11], v60 offset:16384
	s_waitcnt lgkmcnt(3)
	v_mfma_f32_32x32x16_bf16 v[18:33], v[12:15], v[174:177], v[18:33]
	ds_read_b128 v[12:15], v60 offset:24576
	s_waitcnt lgkmcnt(3)
	v_mfma_f32_32x32x16_bf16 v[34:49], v[52:55], v[170:173], v[34:49]
	v_xad_u32 v60, v228, v222, v223
	ds_read_b128 v[52:55], v60 offset:16384
	s_waitcnt lgkmcnt(3)
	v_mfma_f32_32x32x16_bf16 v[18:33], v[56:59], v[170:173], v[18:33]
	ds_read_b128 v[56:59], v60 offset:24576
	s_waitcnt lgkmcnt(3)
	v_mfma_f32_32x32x16_bf16 v[34:49], v[8:11], v[166:169], v[34:49]
	v_xad_u32 v60, v227, v222, v223
	ds_read_b128 v[8:11], v60 offset:16384
	s_waitcnt lgkmcnt(3)
	v_mfma_f32_32x32x16_bf16 v[18:33], v[12:15], v[166:169], v[18:33]
	ds_read_b128 v[12:15], v60 offset:24576
	s_waitcnt lgkmcnt(3)
	v_mfma_f32_32x32x16_bf16 v[34:49], v[52:55], v[162:165], v[34:49]
	v_xad_u32 v60, v226, v222, v223
	ds_read_b128 v[52:55], v60 offset:16384
	s_waitcnt lgkmcnt(3)
	v_mfma_f32_32x32x16_bf16 v[18:33], v[56:59], v[162:165], v[18:33]
	ds_read_b128 v[56:59], v60 offset:24576
	s_waitcnt lgkmcnt(3)
	v_mfma_f32_32x32x16_bf16 v[34:49], v[8:11], v[158:161], v[34:49]
	v_xad_u32 v60, v225, v222, v223
	ds_read_b128 v[8:11], v60 offset:16384
	s_waitcnt lgkmcnt(3)
	v_mfma_f32_32x32x16_bf16 v[18:33], v[12:15], v[158:161], v[18:33]
	ds_read_b128 v[12:15], v60 offset:24576
	s_waitcnt lgkmcnt(3)
	v_mfma_f32_32x32x16_bf16 v[34:49], v[52:55], v[154:157], v[34:49]
	v_xad_u32 v60, v224, v222, v223
	ds_read_b128 v[52:55], v60 offset:16384
	s_waitcnt lgkmcnt(3)
	v_mfma_f32_32x32x16_bf16 v[18:33], v[56:59], v[154:157], v[18:33]
	ds_read_b128 v[56:59], v60 offset:24576
	s_waitcnt lgkmcnt(3)
	v_mfma_f32_32x32x16_bf16 v[34:49], v[8:11], v[150:153], v[34:49]
	s_waitcnt lgkmcnt(2)
	v_mfma_f32_32x32x16_bf16 v[18:33], v[12:15], v[150:153], v[18:33]
	s_waitcnt lgkmcnt(1)
	v_mfma_f32_32x32x16_bf16 v[34:49], v[52:55], v[146:149], v[34:49]
	s_waitcnt lgkmcnt(0)
	v_mfma_f32_32x32x16_bf16 v[18:33], v[56:59], v[146:149], v[18:33]
.LBB0_2281:
	s_waitcnt vmcnt(4)
	s_mov_b64 s[6:7], 0x4440100
	s_mov_b32 m0, s23
	s_waitcnt lgkmcnt(0)
	s_barrier
	v_lshl_add_u64 v[4:5], v[82:83], 0, s[6:7]
	s_mov_b64 s[6:7], 0x4450100
	global_load_lds_dwordx4 v[4:5], off
	v_lshl_add_u64 v[4:5], v[82:83], 0, s[6:7]
	s_mov_b32 m0, s22
	s_and_b64 vcc, exec, s[4:5]
	global_load_lds_dwordx4 v[4:5], off
	s_cbranch_vccnz .LBB0_2283
	v_xad_u32 v92, v231, v222, v223
	ds_read_b128 v[8:11], v92 offset:32768
	ds_read_b128 v[12:15], v92 offset:40960
	v_xad_u32 v92, v230, v222, v223
	ds_read_b128 v[84:87], v92 offset:32768
	ds_read_b128 v[88:91], v92 offset:40960
	s_waitcnt lgkmcnt(3)
	v_mfma_f32_32x32x16_bf16 v[66:81], v[8:11], v[114:117], 0
	v_xad_u32 v92, v229, v222, v223
	ds_read_b128 v[8:11], v92 offset:32768
	s_waitcnt lgkmcnt(3)
	v_mfma_f32_32x32x16_bf16 v[50:65], v[12:15], v[114:117], 0
	ds_read_b128 v[12:15], v92 offset:40960
	s_waitcnt lgkmcnt(3)
	v_mfma_f32_32x32x16_bf16 v[66:81], v[84:87], v[202:205], v[66:81]
	v_xad_u32 v92, v228, v222, v223
	ds_read_b128 v[84:87], v92 offset:32768
	s_waitcnt lgkmcnt(3)
	v_mfma_f32_32x32x16_bf16 v[50:65], v[88:91], v[202:205], v[50:65]
	ds_read_b128 v[88:91], v92 offset:40960
	s_waitcnt lgkmcnt(3)
	v_mfma_f32_32x32x16_bf16 v[66:81], v[8:11], v[198:201], v[66:81]
	v_xad_u32 v92, v227, v222, v223
	ds_read_b128 v[8:11], v92 offset:32768
	s_waitcnt lgkmcnt(3)
	v_mfma_f32_32x32x16_bf16 v[50:65], v[12:15], v[198:201], v[50:65]
	ds_read_b128 v[12:15], v92 offset:40960
	s_waitcnt lgkmcnt(3)
	v_mfma_f32_32x32x16_bf16 v[66:81], v[84:87], v[194:197], v[66:81]
	v_xad_u32 v92, v226, v222, v223
	ds_read_b128 v[84:87], v92 offset:32768
	s_waitcnt lgkmcnt(3)
	v_mfma_f32_32x32x16_bf16 v[50:65], v[88:91], v[194:197], v[50:65]
	ds_read_b128 v[88:91], v92 offset:40960
	s_waitcnt lgkmcnt(3)
	v_mfma_f32_32x32x16_bf16 v[66:81], v[8:11], v[190:193], v[66:81]
	v_xad_u32 v92, v225, v222, v223
	ds_read_b128 v[8:11], v92 offset:32768
	s_waitcnt lgkmcnt(3)
	v_mfma_f32_32x32x16_bf16 v[50:65], v[12:15], v[190:193], v[50:65]
	ds_read_b128 v[12:15], v92 offset:40960
	s_waitcnt lgkmcnt(3)
	v_mfma_f32_32x32x16_bf16 v[66:81], v[84:87], v[186:189], v[66:81]
	v_xad_u32 v92, v224, v222, v223
	ds_read_b128 v[84:87], v92 offset:32768
	s_waitcnt lgkmcnt(3)
	v_mfma_f32_32x32x16_bf16 v[50:65], v[88:91], v[186:189], v[50:65]
	ds_read_b128 v[88:91], v92 offset:40960
	s_waitcnt lgkmcnt(3)
	v_mfma_f32_32x32x16_bf16 v[66:81], v[8:11], v[182:185], v[66:81]
	s_waitcnt lgkmcnt(2)
	v_mfma_f32_32x32x16_bf16 v[50:65], v[12:15], v[182:185], v[50:65]
	s_waitcnt lgkmcnt(1)
	v_mfma_f32_32x32x16_bf16 v[66:81], v[84:87], v[178:181], v[66:81]
	s_waitcnt lgkmcnt(0)
	v_mfma_f32_32x32x16_bf16 v[50:65], v[88:91], v[178:181], v[50:65]
	s_branch .LBB0_2284

.LBB0_2284:
	s_waitcnt vmcnt(4)
	s_mov_b64 s[6:7], 0x4460000
	s_mov_b32 m0, s21
	s_waitcnt lgkmcnt(0)
	s_barrier
	v_lshl_add_u64 v[4:5], v[82:83], 0, s[6:7]
	s_mov_b64 s[6:7], 0x4470000
	global_load_lds_dwordx4 v[4:5], off
	v_lshl_add_u64 v[4:5], v[82:83], 0, s[6:7]
	s_mov_b32 m0, s20
	s_and_b64 vcc, exec, s[4:5]
	global_load_lds_dwordx4 v[4:5], off
	s_cbranch_vccnz .LBB0_2286
	v_xad_u32 v92, v231, v222, v223
	ds_read_b128 v[8:11], v92 offset:49152
	ds_read_b128 v[12:15], v92 offset:57344
	v_xad_u32 v92, v230, v222, v223
	ds_read_b128 v[84:87], v92 offset:49152
	ds_read_b128 v[88:91], v92 offset:57344
	s_waitcnt lgkmcnt(3)
	v_mfma_f32_32x32x16_bf16 v[66:81], v[8:11], v[174:177], v[66:81]
	v_xad_u32 v92, v229, v222, v223
	ds_read_b128 v[8:11], v92 offset:49152
	s_waitcnt lgkmcnt(3)
	v_mfma_f32_32x32x16_bf16 v[50:65], v[12:15], v[174:177], v[50:65]
	ds_read_b128 v[12:15], v92 offset:57344
	s_waitcnt lgkmcnt(3)
	v_mfma_f32_32x32x16_bf16 v[66:81], v[84:87], v[170:173], v[66:81]
	v_xad_u32 v92, v228, v222, v223
	ds_read_b128 v[84:87], v92 offset:49152
	s_waitcnt lgkmcnt(3)
	v_mfma_f32_32x32x16_bf16 v[50:65], v[88:91], v[170:173], v[50:65]
	ds_read_b128 v[88:91], v92 offset:57344
	s_waitcnt lgkmcnt(3)
	v_mfma_f32_32x32x16_bf16 v[66:81], v[8:11], v[166:169], v[66:81]
	v_xad_u32 v92, v227, v222, v223
	ds_read_b128 v[8:11], v92 offset:49152
	s_waitcnt lgkmcnt(3)
	v_mfma_f32_32x32x16_bf16 v[50:65], v[12:15], v[166:169], v[50:65]
	ds_read_b128 v[12:15], v92 offset:57344
	s_waitcnt lgkmcnt(3)
	v_mfma_f32_32x32x16_bf16 v[66:81], v[84:87], v[162:165], v[66:81]
	v_xad_u32 v92, v226, v222, v223
	ds_read_b128 v[84:87], v92 offset:49152
	s_waitcnt lgkmcnt(3)
	v_mfma_f32_32x32x16_bf16 v[50:65], v[88:91], v[162:165], v[50:65]
	ds_read_b128 v[88:91], v92 offset:57344
	s_waitcnt lgkmcnt(3)
	v_mfma_f32_32x32x16_bf16 v[66:81], v[8:11], v[158:161], v[66:81]
	v_xad_u32 v92, v225, v222, v223
	ds_read_b128 v[8:11], v92 offset:49152
	s_waitcnt lgkmcnt(3)
	v_mfma_f32_32x32x16_bf16 v[50:65], v[12:15], v[158:161], v[50:65]
	ds_read_b128 v[12:15], v92 offset:57344
	s_waitcnt lgkmcnt(3)
	v_mfma_f32_32x32x16_bf16 v[66:81], v[84:87], v[154:157], v[66:81]
	v_xad_u32 v92, v224, v222, v223
	ds_read_b128 v[84:87], v92 offset:49152
	s_waitcnt lgkmcnt(3)
	v_mfma_f32_32x32x16_bf16 v[50:65], v[88:91], v[154:157], v[50:65]
	ds_read_b128 v[88:91], v92 offset:57344
	s_waitcnt lgkmcnt(3)
	v_mfma_f32_32x32x16_bf16 v[66:81], v[8:11], v[150:153], v[66:81]
	s_waitcnt lgkmcnt(2)
	v_mfma_f32_32x32x16_bf16 v[50:65], v[12:15], v[150:153], v[50:65]
	s_waitcnt lgkmcnt(1)
	v_mfma_f32_32x32x16_bf16 v[66:81], v[84:87], v[146:149], v[66:81]
	s_waitcnt lgkmcnt(0)
	v_mfma_f32_32x32x16_bf16 v[50:65], v[88:91], v[146:149], v[50:65]
.LBB0_2286:
	s_waitcnt vmcnt(4)
	s_mov_b64 s[6:7], 0x4460100
	s_mov_b32 m0, s19
	s_waitcnt lgkmcnt(0)
	s_barrier
	v_lshl_add_u64 v[4:5], v[82:83], 0, s[6:7]
	s_mov_b64 s[6:7], 0x4470100
	global_load_lds_dwordx4 v[4:5], off
	v_lshl_add_u64 v[4:5], v[82:83], 0, s[6:7]
	s_mov_b32 m0, s18
	s_and_b64 vcc, exec, s[4:5]
	global_load_lds_dwordx4 v[4:5], off
	s_cbranch_vccnz .LBB0_2288
	v_xad_u32 v128, v231, v222, v223
	ds_read_b128 v[8:11], v128
	ds_read_b128 v[12:15], v128 offset:8192
	v_xad_u32 v128, v230, v222, v223
	ds_read_b128 v[120:123], v128
	ds_read_b128 v[124:127], v128 offset:8192
	s_waitcnt lgkmcnt(3)
	v_mfma_f32_32x32x16_bf16 v[98:113], v[8:11], v[114:117], 0
	v_xad_u32 v128, v229, v222, v223
	ds_read_b128 v[8:11], v128
	s_waitcnt lgkmcnt(3)
	v_mfma_f32_32x32x16_bf16 v[82:97], v[12:15], v[114:117], 0
	ds_read_b128 v[12:15], v128 offset:8192
	s_waitcnt lgkmcnt(3)
	v_mfma_f32_32x32x16_bf16 v[98:113], v[120:123], v[202:205], v[98:113]
	v_xad_u32 v128, v228, v222, v223
	ds_read_b128 v[120:123], v128
	s_waitcnt lgkmcnt(3)
	v_mfma_f32_32x32x16_bf16 v[82:97], v[124:127], v[202:205], v[82:97]
	ds_read_b128 v[124:127], v128 offset:8192
	s_waitcnt lgkmcnt(3)
	v_mfma_f32_32x32x16_bf16 v[98:113], v[8:11], v[198:201], v[98:113]
	v_xad_u32 v128, v227, v222, v223
	ds_read_b128 v[8:11], v128
	s_waitcnt lgkmcnt(3)
	v_mfma_f32_32x32x16_bf16 v[82:97], v[12:15], v[198:201], v[82:97]
	ds_read_b128 v[12:15], v128 offset:8192
	s_waitcnt lgkmcnt(3)
	v_mfma_f32_32x32x16_bf16 v[98:113], v[120:123], v[194:197], v[98:113]
	v_xad_u32 v128, v226, v222, v223
	ds_read_b128 v[120:123], v128
	s_waitcnt lgkmcnt(3)
	v_mfma_f32_32x32x16_bf16 v[82:97], v[124:127], v[194:197], v[82:97]
	ds_read_b128 v[124:127], v128 offset:8192
	s_waitcnt lgkmcnt(3)
	v_mfma_f32_32x32x16_bf16 v[98:113], v[8:11], v[190:193], v[98:113]
	v_xad_u32 v128, v225, v222, v223
	ds_read_b128 v[8:11], v128
	s_waitcnt lgkmcnt(3)
	v_mfma_f32_32x32x16_bf16 v[82:97], v[12:15], v[190:193], v[82:97]
	ds_read_b128 v[12:15], v128 offset:8192
	s_waitcnt lgkmcnt(3)
	v_mfma_f32_32x32x16_bf16 v[98:113], v[120:123], v[186:189], v[98:113]
	v_xad_u32 v128, v224, v222, v223
	ds_read_b128 v[120:123], v128
	s_waitcnt lgkmcnt(3)
	v_mfma_f32_32x32x16_bf16 v[82:97], v[124:127], v[186:189], v[82:97]
	ds_read_b128 v[124:127], v128 offset:8192
	s_waitcnt lgkmcnt(3)
	v_mfma_f32_32x32x16_bf16 v[98:113], v[8:11], v[182:185], v[98:113]
	s_waitcnt lgkmcnt(2)
	v_mfma_f32_32x32x16_bf16 v[82:97], v[12:15], v[182:185], v[82:97]
	s_waitcnt lgkmcnt(1)
	v_mfma_f32_32x32x16_bf16 v[98:113], v[120:123], v[178:181], v[98:113]
	s_waitcnt lgkmcnt(0)
	v_mfma_f32_32x32x16_bf16 v[82:97], v[124:127], v[178:181], v[82:97]
	s_branch .LBB0_2289

.LBB0_2289:
	v_and_b32_e32 v219, 63, v118
	v_lshrrev_b32_e32 v2, 2, v219
	v_lshrrev_b32_e32 v4, 1, v219
	s_lshr_b32 s6, s27, 1
	v_lshlrev_b32_e32 v220, 3, v219
	v_bitop3_b32 v2, s27, v216, v2 bitop3:0xc8
	v_and_b32_e32 v4, 8, v4
	s_and_b32 s6, s6, 4
	s_and_b32 s7, s26, 64
	v_and_b32_e32 v221, 24, v220
	v_or3_b32 v2, v2, v4, s6
	v_or3_b32 v4, s7, v217, v221
	v_lshlrev_b32_e32 v4, 1, v4
	s_add_u32 s6, s15, s2
	v_lshl_or_b32 v2, v2, 11, v4
	s_addc_u32 s7, s16, s3
	s_waitcnt vmcnt(4)
	v_lshl_add_u64 v[206:207], s[6:7], 0, v[2:3]
	s_mov_b64 s[6:7], 0x4c00000
	s_mov_b32 m0, s25
	s_waitcnt lgkmcnt(0)
	s_barrier
	v_lshl_add_u64 v[4:5], v[206:207], 0, s[6:7]
	s_mov_b64 s[6:7], 0x4c10000
	global_load_lds_dwordx4 v[4:5], off
	v_lshl_add_u64 v[4:5], v[206:207], 0, s[6:7]
	s_mov_b32 m0, s24
	s_and_b64 vcc, exec, s[4:5]
	global_load_lds_dwordx4 v[4:5], off
	s_cbranch_vccnz .LBB0_2291
	v_xad_u32 v128, v231, v222, v223
	ds_read_b128 v[8:11], v128 offset:16384
	ds_read_b128 v[12:15], v128 offset:24576
	v_xad_u32 v128, v230, v222, v223
	ds_read_b128 v[120:123], v128 offset:16384
	ds_read_b128 v[124:127], v128 offset:24576
	s_waitcnt lgkmcnt(3)
	v_mfma_f32_32x32x16_bf16 v[98:113], v[8:11], v[174:177], v[98:113]
	v_xad_u32 v128, v229, v222, v223
	ds_read_b128 v[8:11], v128 offset:16384
	s_waitcnt lgkmcnt(3)
	v_mfma_f32_32x32x16_bf16 v[82:97], v[12:15], v[174:177], v[82:97]
	ds_read_b128 v[12:15], v128 offset:24576
	s_waitcnt lgkmcnt(3)
	v_mfma_f32_32x32x16_bf16 v[98:113], v[120:123], v[170:173], v[98:113]
	v_xad_u32 v128, v228, v222, v223
	ds_read_b128 v[120:123], v128 offset:16384
	s_waitcnt lgkmcnt(3)
	v_mfma_f32_32x32x16_bf16 v[82:97], v[124:127], v[170:173], v[82:97]
	ds_read_b128 v[124:127], v128 offset:24576
	s_waitcnt lgkmcnt(3)
	v_mfma_f32_32x32x16_bf16 v[98:113], v[8:11], v[166:169], v[98:113]
	v_xad_u32 v128, v227, v222, v223
	ds_read_b128 v[8:11], v128 offset:16384
	s_waitcnt lgkmcnt(3)
	v_mfma_f32_32x32x16_bf16 v[82:97], v[12:15], v[166:169], v[82:97]
	ds_read_b128 v[12:15], v128 offset:24576
	s_waitcnt lgkmcnt(3)
	v_mfma_f32_32x32x16_bf16 v[98:113], v[120:123], v[162:165], v[98:113]
	v_xad_u32 v128, v226, v222, v223
	ds_read_b128 v[120:123], v128 offset:16384
	s_waitcnt lgkmcnt(3)
	v_mfma_f32_32x32x16_bf16 v[82:97], v[124:127], v[162:165], v[82:97]
	ds_read_b128 v[124:127], v128 offset:24576
	s_waitcnt lgkmcnt(3)
	v_mfma_f32_32x32x16_bf16 v[98:113], v[8:11], v[158:161], v[98:113]
	v_xad_u32 v128, v225, v222, v223
	ds_read_b128 v[8:11], v128 offset:16384
	s_waitcnt lgkmcnt(3)
	v_mfma_f32_32x32x16_bf16 v[82:97], v[12:15], v[158:161], v[82:97]
	ds_read_b128 v[12:15], v128 offset:24576
	s_waitcnt lgkmcnt(3)
	v_mfma_f32_32x32x16_bf16 v[98:113], v[120:123], v[154:157], v[98:113]
	v_xad_u32 v128, v224, v222, v223
	ds_read_b128 v[120:123], v128 offset:16384
	s_waitcnt lgkmcnt(3)
	v_mfma_f32_32x32x16_bf16 v[82:97], v[124:127], v[154:157], v[82:97]
	ds_read_b128 v[124:127], v128 offset:24576
	s_waitcnt lgkmcnt(3)
	v_mfma_f32_32x32x16_bf16 v[98:113], v[8:11], v[150:153], v[98:113]
	s_waitcnt lgkmcnt(2)
	v_mfma_f32_32x32x16_bf16 v[82:97], v[12:15], v[150:153], v[82:97]
	s_waitcnt lgkmcnt(1)
	v_mfma_f32_32x32x16_bf16 v[98:113], v[120:123], v[146:149], v[98:113]
	s_waitcnt lgkmcnt(0)
	v_mfma_f32_32x32x16_bf16 v[82:97], v[124:127], v[146:149], v[82:97]
.LBB0_2291:
	s_waitcnt vmcnt(4)
	s_mov_b64 s[6:7], 0x4c20000
	s_mov_b32 m0, s23
	s_waitcnt lgkmcnt(0)
	s_barrier
	v_lshl_add_u64 v[4:5], v[206:207], 0, s[6:7]
	s_mov_b64 s[6:7], 0x4c30000
	global_load_lds_dwordx4 v[4:5], off
	v_lshl_add_u64 v[4:5], v[206:207], 0, s[6:7]
	s_mov_b32 m0, s22
	s_and_b64 vcc, exec, s[4:5]
	global_load_lds_dwordx4 v[4:5], off
	s_cbranch_vccnz .LBB0_2293
	v_xad_u32 v240, v231, v222, v223
	ds_read_b128 v[8:11], v240 offset:32768
	ds_read_b128 v[12:15], v240 offset:40960
	v_xad_u32 v240, v230, v222, v223
	ds_read_b128 v[232:235], v240 offset:32768
	ds_read_b128 v[236:239], v240 offset:40960
	s_waitcnt lgkmcnt(3)
	v_mfma_f32_32x32x16_bf16 v[130:145], v[8:11], v[114:117], 0
	v_xad_u32 v240, v229, v222, v223
	ds_read_b128 v[8:11], v240 offset:32768
	s_waitcnt lgkmcnt(3)
	v_mfma_f32_32x32x16_bf16 v[114:129], v[12:15], v[114:117], 0
	ds_read_b128 v[12:15], v240 offset:40960
	s_waitcnt lgkmcnt(3)
	v_mfma_f32_32x32x16_bf16 v[130:145], v[232:235], v[202:205], v[130:145]
	v_xad_u32 v240, v228, v222, v223
	ds_read_b128 v[232:235], v240 offset:32768
	s_waitcnt lgkmcnt(3)
	v_mfma_f32_32x32x16_bf16 v[114:129], v[236:239], v[202:205], v[114:129]
	ds_read_b128 v[236:239], v240 offset:40960
	s_waitcnt lgkmcnt(3)
	v_mfma_f32_32x32x16_bf16 v[130:145], v[8:11], v[198:201], v[130:145]
	v_xad_u32 v240, v227, v222, v223
	ds_read_b128 v[8:11], v240 offset:32768
	s_waitcnt lgkmcnt(3)
	v_mfma_f32_32x32x16_bf16 v[114:129], v[12:15], v[198:201], v[114:129]
	ds_read_b128 v[12:15], v240 offset:40960
	s_waitcnt lgkmcnt(3)
	v_mfma_f32_32x32x16_bf16 v[130:145], v[232:235], v[194:197], v[130:145]
	v_xad_u32 v240, v226, v222, v223
	ds_read_b128 v[232:235], v240 offset:32768
	s_waitcnt lgkmcnt(3)
	v_mfma_f32_32x32x16_bf16 v[114:129], v[236:239], v[194:197], v[114:129]
	ds_read_b128 v[236:239], v240 offset:40960
	s_waitcnt lgkmcnt(3)
	v_mfma_f32_32x32x16_bf16 v[130:145], v[8:11], v[190:193], v[130:145]
	v_xad_u32 v240, v225, v222, v223
	ds_read_b128 v[8:11], v240 offset:32768
	s_waitcnt lgkmcnt(3)
	v_mfma_f32_32x32x16_bf16 v[114:129], v[12:15], v[190:193], v[114:129]
	ds_read_b128 v[12:15], v240 offset:40960
	s_waitcnt lgkmcnt(3)
	v_mfma_f32_32x32x16_bf16 v[130:145], v[232:235], v[186:189], v[130:145]
	v_xad_u32 v240, v224, v222, v223
	ds_read_b128 v[232:235], v240 offset:32768
	s_waitcnt lgkmcnt(3)
	v_mfma_f32_32x32x16_bf16 v[114:129], v[236:239], v[186:189], v[114:129]
	ds_read_b128 v[236:239], v240 offset:40960
	s_waitcnt lgkmcnt(3)
	v_mfma_f32_32x32x16_bf16 v[130:145], v[8:11], v[182:185], v[130:145]
	s_waitcnt lgkmcnt(2)
	v_mfma_f32_32x32x16_bf16 v[114:129], v[12:15], v[182:185], v[114:129]
	s_waitcnt lgkmcnt(1)
	v_mfma_f32_32x32x16_bf16 v[130:145], v[232:235], v[178:181], v[130:145]
	s_waitcnt lgkmcnt(0)
	v_mfma_f32_32x32x16_bf16 v[114:129], v[236:239], v[178:181], v[114:129]
	s_branch .LBB0_2294

.LBB0_2294:
	s_waitcnt vmcnt(4)
	s_mov_b64 s[6:7], 0x4c40000
	s_mov_b32 m0, s21
	s_waitcnt lgkmcnt(0)
	s_barrier
	v_lshl_add_u64 v[4:5], v[206:207], 0, s[6:7]
	s_mov_b64 s[6:7], 0x4c50000
	global_load_lds_dwordx4 v[4:5], off
	v_lshl_add_u64 v[4:5], v[206:207], 0, s[6:7]
	s_mov_b32 m0, s20
	s_and_b64 vcc, exec, s[4:5]
	global_load_lds_dwordx4 v[4:5], off
	s_cbranch_vccnz .LBB0_2296
	v_xad_u32 v188, v231, v222, v223
	ds_read_b128 v[8:11], v188 offset:49152
	ds_read_b128 v[12:15], v188 offset:57344
	v_xad_u32 v188, v230, v222, v223
	ds_read_b128 v[180:183], v188 offset:49152
	ds_read_b128 v[184:187], v188 offset:57344
	s_waitcnt lgkmcnt(3)
	v_mfma_f32_32x32x16_bf16 v[130:145], v[8:11], v[174:177], v[130:145]
	v_xad_u32 v188, v229, v222, v223
	ds_read_b128 v[8:11], v188 offset:49152
	s_waitcnt lgkmcnt(3)
	v_mfma_f32_32x32x16_bf16 v[114:129], v[12:15], v[174:177], v[114:129]
	ds_read_b128 v[12:15], v188 offset:57344
	s_waitcnt lgkmcnt(3)
	v_mfma_f32_32x32x16_bf16 v[130:145], v[180:183], v[170:173], v[130:145]
	v_xad_u32 v188, v228, v222, v223
	ds_read_b128 v[180:183], v188 offset:49152
	s_waitcnt lgkmcnt(3)
	v_mfma_f32_32x32x16_bf16 v[114:129], v[184:187], v[170:173], v[114:129]
	ds_read_b128 v[184:187], v188 offset:57344
	s_waitcnt lgkmcnt(3)
	v_mfma_f32_32x32x16_bf16 v[130:145], v[8:11], v[166:169], v[130:145]
	v_xad_u32 v188, v227, v222, v223
	ds_read_b128 v[8:11], v188 offset:49152
	s_waitcnt lgkmcnt(3)
	v_mfma_f32_32x32x16_bf16 v[114:129], v[12:15], v[166:169], v[114:129]
	ds_read_b128 v[12:15], v188 offset:57344
	s_waitcnt lgkmcnt(3)
	v_mfma_f32_32x32x16_bf16 v[130:145], v[180:183], v[162:165], v[130:145]
	v_xad_u32 v188, v226, v222, v223
	ds_read_b128 v[180:183], v188 offset:49152
	s_waitcnt lgkmcnt(3)
	v_mfma_f32_32x32x16_bf16 v[114:129], v[184:187], v[162:165], v[114:129]
	ds_read_b128 v[184:187], v188 offset:57344
	s_waitcnt lgkmcnt(3)
	v_mfma_f32_32x32x16_bf16 v[130:145], v[8:11], v[158:161], v[130:145]
	v_xad_u32 v188, v225, v222, v223
	ds_read_b128 v[8:11], v188 offset:49152
	s_waitcnt lgkmcnt(3)
	v_mfma_f32_32x32x16_bf16 v[114:129], v[12:15], v[158:161], v[114:129]
	ds_read_b128 v[12:15], v188 offset:57344
	s_waitcnt lgkmcnt(3)
	v_mfma_f32_32x32x16_bf16 v[130:145], v[180:183], v[154:157], v[130:145]
	v_xad_u32 v188, v224, v222, v223
	ds_read_b128 v[180:183], v188 offset:49152
	s_waitcnt lgkmcnt(3)
	v_mfma_f32_32x32x16_bf16 v[114:129], v[184:187], v[154:157], v[114:129]
	ds_read_b128 v[184:187], v188 offset:57344
	s_waitcnt lgkmcnt(3)
	v_mfma_f32_32x32x16_bf16 v[130:145], v[8:11], v[150:153], v[130:145]
	s_waitcnt lgkmcnt(2)
	v_mfma_f32_32x32x16_bf16 v[114:129], v[12:15], v[150:153], v[114:129]
	s_waitcnt lgkmcnt(1)
	v_mfma_f32_32x32x16_bf16 v[130:145], v[180:183], v[146:149], v[130:145]
	s_waitcnt lgkmcnt(0)
	v_mfma_f32_32x32x16_bf16 v[114:129], v[184:187], v[146:149], v[114:129]

.LBB0_2320:
	v_readlane_b32 s12, v255, 43
	v_readlane_b32 s13, v255, 44
	s_lshl_b64 s[12:13], s[12:13], 24
	s_waitcnt lgkmcnt(0)
	s_add_u32 s5, s0, s12
	s_addc_u32 s11, s1, s13
	s_ashr_i32 s7, s6, 31
	s_lshl_b64 s[12:13], s[6:7], 19
	s_add_u32 s5, s5, s12
	s_addc_u32 s12, s11, s13
	s_lshl_b32 s21, s10, 2
	s_lshl_b32 s11, s4, 1
	s_add_u32 s4, s5, s11
	v_and_b32_e32 v195, 63, v104
	s_addc_u32 s5, s12, 0
	v_lshrrev_b32_e32 v4, 4, v195
	s_add_u32 s4, s4, 0x5400000
	v_or_b32_e32 v4, s21, v4
	v_and_b32_e32 v6, 15, v104
	s_addc_u32 s5, s5, 0
	s_lshl_b32 s12, s10, 10
	v_lshlrev_b32_e32 v5, 11, v4
	v_bitop3_b32 v4, v4, v6, 7 bitop3:0x6c
	s_add_i32 s19, s12, 0
	v_lshl_or_b32 v4, v4, 4, v5
	v_mov_b32_e32 v5, v3
	s_mov_b32 m0, s19
	v_lshl_add_u64 v[68:69], s[4:5], 0, v[4:5]
	global_load_lds_dwordx4 v4, s[4:5]
	s_mov_b64 s[4:5], 0x10000
	s_add_i32 s18, s19, 0x2000
	v_lshl_add_u64 v[4:5], v[68:69], 0, s[4:5]
	s_mov_b32 m0, s18
	s_add_i32 s17, s19, 0x4000
	global_load_lds_dwordx4 v[4:5], off
	v_lshl_add_u64 v[4:5], v[68:69], 0, s[86:87]
	s_mov_b32 m0, s17
	s_mov_b64 s[4:5], 0x10100
	s_add_i32 s16, s19, 0x6000
	global_load_lds_dwordx4 v[4:5], off
	v_lshl_add_u64 v[4:5], v[68:69], 0, s[4:5]
	s_mov_b32 m0, s16
	s_mov_b64 s[4:5], 0x20000
	s_add_i32 s15, s19, 0x8000
	global_load_lds_dwordx4 v[4:5], off
	v_lshl_add_u64 v[4:5], v[68:69], 0, s[4:5]
	s_mov_b32 m0, s15
	s_mov_b64 s[4:5], 0x30000
	s_add_i32 s14, s19, 0xa000
	global_load_lds_dwordx4 v[4:5], off
	v_lshl_add_u64 v[4:5], v[68:69], 0, s[4:5]
	s_mov_b32 m0, s14
	s_mov_b64 s[4:5], 0x20100
	global_load_lds_dwordx4 v[4:5], off
	s_waitcnt vmcnt(4)
	s_add_i32 s13, s19, 0xc000
	s_waitcnt lgkmcnt(0)
	s_barrier
	v_lshl_add_u64 v[4:5], v[68:69], 0, s[4:5]
	s_mov_b32 m0, s13
	s_mov_b64 s[4:5], 0x30100
	s_add_i32 s12, s19, 0xe000
	global_load_lds_dwordx4 v[4:5], off
	v_lshl_add_u64 v[4:5], v[68:69], 0, s[4:5]
	s_mov_b32 m0, s12
	s_andn2_b64 vcc, exec, s[8:9]
	global_load_lds_dwordx4 v[4:5], off
	v_cndmask_b32_e64 v4, 0, 1, s[8:9]
	v_cmp_ne_u32_e64 s[4:5], 1, v4
	v_lshlrev_b32_e32 v4, 4, v1
	v_and_b32_e32 v198, 0x70, v4
	v_lshl_add_u32 v199, v1, 8, 0
	v_or_b32_e32 v206, 32, v194
	v_or_b32_e32 v205, 64, v194
	v_or_b32_e32 v204, 0x60, v194
	v_or_b32_e32 v203, 0x80, v194
	v_or_b32_e32 v202, 0xa0, v194
	v_or_b32_e32 v201, 0xc0, v194
	v_or_b32_e32 v200, 0xe0, v194
	s_cbranch_vccnz .LBB0_2322
	v_xad_u32 v60, v194, v198, v199
	ds_read_b128 v[44:47], v60
	v_xad_u32 v60, v206, v198, v199
	ds_read_b128 v[48:51], v60
	v_xad_u32 v60, v194, v198, v199
	ds_read_b128 v[52:55], v60 offset:8192
	v_xad_u32 v60, v206, v198, v199
	ds_read_b128 v[56:59], v60 offset:8192
	s_waitcnt vmcnt(8) lgkmcnt(3)
	v_mfma_f32_32x32x16_bf16 v[20:35], v[44:47], v[100:103], 0
	v_xad_u32 v60, v205, v198, v199
	ds_read_b128 v[44:47], v60
	s_waitcnt lgkmcnt(3)
	v_mfma_f32_32x32x16_bf16 v[20:35], v[48:51], v[188:191], v[20:35]
	ds_read_b128 v[48:51], v60 offset:8192
	s_waitcnt lgkmcnt(3)
	v_mfma_f32_32x32x16_bf16 v[4:19], v[52:55], v[100:103], 0
	v_xad_u32 v60, v204, v198, v199
	ds_read_b128 v[52:55], v60
	s_waitcnt lgkmcnt(3)
	v_mfma_f32_32x32x16_bf16 v[4:19], v[56:59], v[188:191], v[4:19]
	ds_read_b128 v[56:59], v60 offset:8192
	s_waitcnt lgkmcnt(3)
	v_mfma_f32_32x32x16_bf16 v[20:35], v[44:47], v[184:187], v[20:35]
	v_xad_u32 v60, v203, v198, v199
	ds_read_b128 v[44:47], v60
	s_waitcnt lgkmcnt(3)
	v_mfma_f32_32x32x16_bf16 v[4:19], v[48:51], v[184:187], v[4:19]
	ds_read_b128 v[48:51], v60 offset:8192
	s_waitcnt lgkmcnt(3)
	v_mfma_f32_32x32x16_bf16 v[20:35], v[52:55], v[180:183], v[20:35]
	v_xad_u32 v60, v202, v198, v199
	ds_read_b128 v[52:55], v60
	s_waitcnt lgkmcnt(3)
	v_mfma_f32_32x32x16_bf16 v[4:19], v[56:59], v[180:183], v[4:19]
	ds_read_b128 v[56:59], v60 offset:8192
	s_waitcnt lgkmcnt(3)
	v_mfma_f32_32x32x16_bf16 v[20:35], v[44:47], v[176:179], v[20:35]
	v_xad_u32 v60, v201, v198, v199
	ds_read_b128 v[44:47], v60
	s_waitcnt lgkmcnt(3)
	v_mfma_f32_32x32x16_bf16 v[4:19], v[48:51], v[176:179], v[4:19]
	ds_read_b128 v[48:51], v60 offset:8192
	s_waitcnt lgkmcnt(3)
	v_mfma_f32_32x32x16_bf16 v[20:35], v[52:55], v[172:175], v[20:35]
	v_xad_u32 v60, v200, v198, v199
	ds_read_b128 v[52:55], v60
	s_waitcnt lgkmcnt(3)
	v_mfma_f32_32x32x16_bf16 v[4:19], v[56:59], v[172:175], v[4:19]
	ds_read_b128 v[56:59], v60 offset:8192
	s_waitcnt lgkmcnt(3)
	v_mfma_f32_32x32x16_bf16 v[20:35], v[44:47], v[168:171], v[20:35]
	s_waitcnt lgkmcnt(2)
	v_mfma_f32_32x32x16_bf16 v[4:19], v[48:51], v[168:171], v[4:19]
	s_waitcnt lgkmcnt(1)
	v_mfma_f32_32x32x16_bf16 v[20:35], v[52:55], v[164:167], v[20:35]
	s_waitcnt lgkmcnt(0)
	v_mfma_f32_32x32x16_bf16 v[4:19], v[56:59], v[164:167], v[4:19]
	s_branch .LBB0_2323

.LBB0_2323:
	s_waitcnt vmcnt(4)
	s_mov_b32 m0, s19
	s_waitcnt lgkmcnt(0)
	s_barrier
	v_lshl_add_u64 v[36:37], v[68:69], 0, s[54:55]
	s_mov_b64 s[8:9], 0x50000
	global_load_lds_dwordx4 v[36:37], off
	v_lshl_add_u64 v[36:37], v[68:69], 0, s[8:9]
	s_mov_b32 m0, s18
	s_and_b64 vcc, exec, s[4:5]
	global_load_lds_dwordx4 v[36:37], off
	s_cbranch_vccnz .LBB0_2325
	v_xad_u32 v60, v194, v198, v199
	ds_read_b128 v[44:47], v60 offset:16384
	ds_read_b128 v[48:51], v60 offset:24576
	v_xad_u32 v60, v206, v198, v199
	ds_read_b128 v[52:55], v60 offset:16384
	ds_read_b128 v[56:59], v60 offset:24576
	s_waitcnt lgkmcnt(3)
	v_mfma_f32_32x32x16_bf16 v[20:35], v[44:47], v[160:163], v[20:35]
	v_xad_u32 v60, v205, v198, v199
	ds_read_b128 v[44:47], v60 offset:16384
	s_waitcnt lgkmcnt(3)
	v_mfma_f32_32x32x16_bf16 v[4:19], v[48:51], v[160:163], v[4:19]
	ds_read_b128 v[48:51], v60 offset:24576
	s_waitcnt lgkmcnt(3)
	v_mfma_f32_32x32x16_bf16 v[20:35], v[52:55], v[156:159], v[20:35]
	v_xad_u32 v60, v204, v198, v199
	ds_read_b128 v[52:55], v60 offset:16384
	s_waitcnt lgkmcnt(3)
	v_mfma_f32_32x32x16_bf16 v[4:19], v[56:59], v[156:159], v[4:19]
	ds_read_b128 v[56:59], v60 offset:24576
	s_waitcnt lgkmcnt(3)
	v_mfma_f32_32x32x16_bf16 v[20:35], v[44:47], v[152:155], v[20:35]
	v_xad_u32 v60, v203, v198, v199
	ds_read_b128 v[44:47], v60 offset:16384
	s_waitcnt lgkmcnt(3)
	v_mfma_f32_32x32x16_bf16 v[4:19], v[48:51], v[152:155], v[4:19]
	ds_read_b128 v[48:51], v60 offset:24576
	s_waitcnt lgkmcnt(3)
	v_mfma_f32_32x32x16_bf16 v[20:35], v[52:55], v[148:151], v[20:35]
	v_xad_u32 v60, v202, v198, v199
	ds_read_b128 v[52:55], v60 offset:16384
	s_waitcnt lgkmcnt(3)
	v_mfma_f32_32x32x16_bf16 v[4:19], v[56:59], v[148:151], v[4:19]
	ds_read_b128 v[56:59], v60 offset:24576
	s_waitcnt lgkmcnt(3)
	v_mfma_f32_32x32x16_bf16 v[20:35], v[44:47], v[144:147], v[20:35]
	v_xad_u32 v60, v201, v198, v199
	ds_read_b128 v[44:47], v60 offset:16384
	s_waitcnt lgkmcnt(3)
	v_mfma_f32_32x32x16_bf16 v[4:19], v[48:51], v[144:147], v[4:19]
	ds_read_b128 v[48:51], v60 offset:24576
	s_waitcnt lgkmcnt(3)
	v_mfma_f32_32x32x16_bf16 v[20:35], v[52:55], v[140:143], v[20:35]
	v_xad_u32 v60, v200, v198, v199
	ds_read_b128 v[52:55], v60 offset:16384
	s_waitcnt lgkmcnt(3)
	v_mfma_f32_32x32x16_bf16 v[4:19], v[56:59], v[140:143], v[4:19]
	ds_read_b128 v[56:59], v60 offset:24576
	s_waitcnt lgkmcnt(3)
	v_mfma_f32_32x32x16_bf16 v[20:35], v[44:47], v[136:139], v[20:35]
	s_waitcnt lgkmcnt(2)
	v_mfma_f32_32x32x16_bf16 v[4:19], v[48:51], v[136:139], v[4:19]
	s_waitcnt lgkmcnt(1)
	v_mfma_f32_32x32x16_bf16 v[20:35], v[52:55], v[132:135], v[20:35]
	s_waitcnt lgkmcnt(0)
	v_mfma_f32_32x32x16_bf16 v[4:19], v[56:59], v[132:135], v[4:19]
.LBB0_2325:
	s_waitcnt vmcnt(4)
	s_mov_b64 s[8:9], 0x40100
	s_mov_b32 m0, s17
	s_waitcnt lgkmcnt(0)
	s_barrier
	v_lshl_add_u64 v[36:37], v[68:69], 0, s[8:9]
	s_mov_b64 s[8:9], 0x50100
	global_load_lds_dwordx4 v[36:37], off
	v_lshl_add_u64 v[36:37], v[68:69], 0, s[8:9]
	s_mov_b32 m0, s16
	s_and_b64 vcc, exec, s[4:5]
	global_load_lds_dwordx4 v[36:37], off
	s_cbranch_vccnz .LBB0_2327
	v_xad_u32 v92, v194, v198, v199
	ds_read_b128 v[76:79], v92 offset:32768
	v_xad_u32 v92, v206, v198, v199
	ds_read_b128 v[80:83], v92 offset:32768
	v_xad_u32 v92, v194, v198, v199
	ds_read_b128 v[84:87], v92 offset:40960
	v_xad_u32 v92, v206, v198, v199
	ds_read_b128 v[88:91], v92 offset:40960
	s_waitcnt lgkmcnt(3)
	v_mfma_f32_32x32x16_bf16 v[52:67], v[76:79], v[100:103], 0
	v_xad_u32 v92, v205, v198, v199
	ds_read_b128 v[76:79], v92 offset:32768
	s_waitcnt lgkmcnt(3)
	v_mfma_f32_32x32x16_bf16 v[52:67], v[80:83], v[188:191], v[52:67]
	ds_read_b128 v[80:83], v92 offset:40960
	s_waitcnt lgkmcnt(3)
	v_mfma_f32_32x32x16_bf16 v[36:51], v[84:87], v[100:103], 0
	v_xad_u32 v92, v204, v198, v199
	ds_read_b128 v[84:87], v92 offset:32768
	s_waitcnt lgkmcnt(3)
	v_mfma_f32_32x32x16_bf16 v[36:51], v[88:91], v[188:191], v[36:51]
	ds_read_b128 v[88:91], v92 offset:40960
	s_waitcnt lgkmcnt(3)
	v_mfma_f32_32x32x16_bf16 v[52:67], v[76:79], v[184:187], v[52:67]
	v_xad_u32 v92, v203, v198, v199
	ds_read_b128 v[76:79], v92 offset:32768
	s_waitcnt lgkmcnt(3)
	v_mfma_f32_32x32x16_bf16 v[36:51], v[80:83], v[184:187], v[36:51]
	ds_read_b128 v[80:83], v92 offset:40960
	s_waitcnt lgkmcnt(3)
	v_mfma_f32_32x32x16_bf16 v[52:67], v[84:87], v[180:183], v[52:67]
	v_xad_u32 v92, v202, v198, v199
	ds_read_b128 v[84:87], v92 offset:32768
	s_waitcnt lgkmcnt(3)
	v_mfma_f32_32x32x16_bf16 v[36:51], v[88:91], v[180:183], v[36:51]
	ds_read_b128 v[88:91], v92 offset:40960
	s_waitcnt lgkmcnt(3)
	v_mfma_f32_32x32x16_bf16 v[52:67], v[76:79], v[176:179], v[52:67]
	v_xad_u32 v92, v201, v198, v199
	ds_read_b128 v[76:79], v92 offset:32768
	s_waitcnt lgkmcnt(3)
	v_mfma_f32_32x32x16_bf16 v[36:51], v[80:83], v[176:179], v[36:51]
	ds_read_b128 v[80:83], v92 offset:40960
	s_waitcnt lgkmcnt(3)
	v_mfma_f32_32x32x16_bf16 v[52:67], v[84:87], v[172:175], v[52:67]
	v_xad_u32 v92, v200, v198, v199
	ds_read_b128 v[84:87], v92 offset:32768
	s_waitcnt lgkmcnt(3)
	v_mfma_f32_32x32x16_bf16 v[36:51], v[88:91], v[172:175], v[36:51]
	ds_read_b128 v[88:91], v92 offset:40960
	s_waitcnt lgkmcnt(3)
	v_mfma_f32_32x32x16_bf16 v[52:67], v[76:79], v[168:171], v[52:67]
	s_waitcnt lgkmcnt(2)
	v_mfma_f32_32x32x16_bf16 v[36:51], v[80:83], v[168:171], v[36:51]
	s_waitcnt lgkmcnt(1)
	v_mfma_f32_32x32x16_bf16 v[52:67], v[84:87], v[164:167], v[52:67]
	s_waitcnt lgkmcnt(0)
	v_mfma_f32_32x32x16_bf16 v[36:51], v[88:91], v[164:167], v[36:51]
	s_branch .LBB0_2328

.LBB0_2328:
	s_waitcnt vmcnt(4)
	s_mov_b32 m0, s15
	s_waitcnt lgkmcnt(0)
	s_barrier
	v_lshl_add_u64 v[70:71], v[68:69], 0, s[22:23]
	s_mov_b64 s[8:9], 0x70000
	global_load_lds_dwordx4 v[70:71], off
	v_lshl_add_u64 v[70:71], v[68:69], 0, s[8:9]
	s_mov_b32 m0, s14
	s_and_b64 vcc, exec, s[4:5]
	global_load_lds_dwordx4 v[70:71], off
	s_cbranch_vccnz .LBB0_2330
	v_xad_u32 v92, v194, v198, v199
	ds_read_b128 v[76:79], v92 offset:49152
	ds_read_b128 v[80:83], v92 offset:57344
	v_xad_u32 v92, v206, v198, v199
	ds_read_b128 v[84:87], v92 offset:49152
	ds_read_b128 v[88:91], v92 offset:57344
	s_waitcnt lgkmcnt(3)
	v_mfma_f32_32x32x16_bf16 v[52:67], v[76:79], v[160:163], v[52:67]
	v_xad_u32 v92, v205, v198, v199
	ds_read_b128 v[76:79], v92 offset:49152
	s_waitcnt lgkmcnt(3)
	v_mfma_f32_32x32x16_bf16 v[36:51], v[80:83], v[160:163], v[36:51]
	ds_read_b128 v[80:83], v92 offset:57344
	s_waitcnt lgkmcnt(3)
	v_mfma_f32_32x32x16_bf16 v[52:67], v[84:87], v[156:159], v[52:67]
	v_xad_u32 v92, v204, v198, v199
	ds_read_b128 v[84:87], v92 offset:49152
	s_waitcnt lgkmcnt(3)
	v_mfma_f32_32x32x16_bf16 v[36:51], v[88:91], v[156:159], v[36:51]
	ds_read_b128 v[88:91], v92 offset:57344
	s_waitcnt lgkmcnt(3)
	v_mfma_f32_32x32x16_bf16 v[52:67], v[76:79], v[152:155], v[52:67]
	v_xad_u32 v92, v203, v198, v199
	ds_read_b128 v[76:79], v92 offset:49152
	s_waitcnt lgkmcnt(3)
	v_mfma_f32_32x32x16_bf16 v[36:51], v[80:83], v[152:155], v[36:51]
	ds_read_b128 v[80:83], v92 offset:57344
	s_waitcnt lgkmcnt(3)
	v_mfma_f32_32x32x16_bf16 v[52:67], v[84:87], v[148:151], v[52:67]
	v_xad_u32 v92, v202, v198, v199
	ds_read_b128 v[84:87], v92 offset:49152
	s_waitcnt lgkmcnt(3)
	v_mfma_f32_32x32x16_bf16 v[36:51], v[88:91], v[148:151], v[36:51]
	ds_read_b128 v[88:91], v92 offset:57344
	s_waitcnt lgkmcnt(3)
	v_mfma_f32_32x32x16_bf16 v[52:67], v[76:79], v[144:147], v[52:67]
	v_xad_u32 v92, v201, v198, v199
	ds_read_b128 v[76:79], v92 offset:49152
	s_waitcnt lgkmcnt(3)
	v_mfma_f32_32x32x16_bf16 v[36:51], v[80:83], v[144:147], v[36:51]
	ds_read_b128 v[80:83], v92 offset:57344
	s_waitcnt lgkmcnt(3)
	v_mfma_f32_32x32x16_bf16 v[52:67], v[84:87], v[140:143], v[52:67]
	v_xad_u32 v92, v200, v198, v199
	ds_read_b128 v[84:87], v92 offset:49152
	s_waitcnt lgkmcnt(3)
	v_mfma_f32_32x32x16_bf16 v[36:51], v[88:91], v[140:143], v[36:51]
	ds_read_b128 v[88:91], v92 offset:57344
	s_waitcnt lgkmcnt(3)
	v_mfma_f32_32x32x16_bf16 v[52:67], v[76:79], v[136:139], v[52:67]
	s_waitcnt lgkmcnt(2)
	v_mfma_f32_32x32x16_bf16 v[36:51], v[80:83], v[136:139], v[36:51]
	s_waitcnt lgkmcnt(1)
	v_mfma_f32_32x32x16_bf16 v[52:67], v[84:87], v[132:135], v[52:67]
	s_waitcnt lgkmcnt(0)
	v_mfma_f32_32x32x16_bf16 v[36:51], v[88:91], v[132:135], v[36:51]
.LBB0_2330:
	s_waitcnt vmcnt(4)
	s_mov_b64 s[8:9], 0x60100
	s_mov_b32 m0, s13
	s_waitcnt lgkmcnt(0)
	s_barrier
	v_lshl_add_u64 v[70:71], v[68:69], 0, s[8:9]
	s_mov_b64 s[8:9], 0x70100
	global_load_lds_dwordx4 v[70:71], off
	v_lshl_add_u64 v[68:69], v[68:69], 0, s[8:9]
	s_mov_b32 m0, s12
	s_and_b64 vcc, exec, s[4:5]
	global_load_lds_dwordx4 v[68:69], off
	s_cbranch_vccnz .LBB0_2332
	v_xad_u32 v128, v194, v198, v199
	ds_read_b128 v[112:115], v128
	v_xad_u32 v128, v206, v198, v199
	ds_read_b128 v[116:119], v128
	v_xad_u32 v128, v194, v198, v199
	ds_read_b128 v[120:123], v128 offset:8192
	v_xad_u32 v128, v206, v198, v199
	ds_read_b128 v[124:127], v128 offset:8192
	s_waitcnt lgkmcnt(3)
	v_mfma_f32_32x32x16_bf16 v[84:99], v[112:115], v[100:103], 0
	v_xad_u32 v128, v205, v198, v199
	ds_read_b128 v[112:115], v128
	s_waitcnt lgkmcnt(3)
	v_mfma_f32_32x32x16_bf16 v[84:99], v[116:119], v[188:191], v[84:99]
	ds_read_b128 v[116:119], v128 offset:8192
	s_waitcnt lgkmcnt(3)
	v_mfma_f32_32x32x16_bf16 v[68:83], v[120:123], v[100:103], 0
	v_xad_u32 v128, v204, v198, v199
	ds_read_b128 v[120:123], v128
	s_waitcnt lgkmcnt(3)
	v_mfma_f32_32x32x16_bf16 v[68:83], v[124:127], v[188:191], v[68:83]
	ds_read_b128 v[124:127], v128 offset:8192
	s_waitcnt lgkmcnt(3)
	v_mfma_f32_32x32x16_bf16 v[84:99], v[112:115], v[184:187], v[84:99]
	v_xad_u32 v128, v203, v198, v199
	ds_read_b128 v[112:115], v128
	s_waitcnt lgkmcnt(3)
	v_mfma_f32_32x32x16_bf16 v[68:83], v[116:119], v[184:187], v[68:83]
	ds_read_b128 v[116:119], v128 offset:8192
	s_waitcnt lgkmcnt(3)
	v_mfma_f32_32x32x16_bf16 v[84:99], v[120:123], v[180:183], v[84:99]
	v_xad_u32 v128, v202, v198, v199
	ds_read_b128 v[120:123], v128
	s_waitcnt lgkmcnt(3)
	v_mfma_f32_32x32x16_bf16 v[68:83], v[124:127], v[180:183], v[68:83]
	ds_read_b128 v[124:127], v128 offset:8192
	s_waitcnt lgkmcnt(3)
	v_mfma_f32_32x32x16_bf16 v[84:99], v[112:115], v[176:179], v[84:99]
	v_xad_u32 v128, v201, v198, v199
	ds_read_b128 v[112:115], v128
	s_waitcnt lgkmcnt(3)
	v_mfma_f32_32x32x16_bf16 v[68:83], v[116:119], v[176:179], v[68:83]
	ds_read_b128 v[116:119], v128 offset:8192
	s_waitcnt lgkmcnt(3)
	v_mfma_f32_32x32x16_bf16 v[84:99], v[120:123], v[172:175], v[84:99]
	v_xad_u32 v128, v200, v198, v199
	ds_read_b128 v[120:123], v128
	s_waitcnt lgkmcnt(3)
	v_mfma_f32_32x32x16_bf16 v[68:83], v[124:127], v[172:175], v[68:83]
	ds_read_b128 v[124:127], v128 offset:8192
	s_waitcnt lgkmcnt(3)
	v_mfma_f32_32x32x16_bf16 v[84:99], v[112:115], v[168:171], v[84:99]
	s_waitcnt lgkmcnt(2)
	v_mfma_f32_32x32x16_bf16 v[68:83], v[116:119], v[168:171], v[68:83]
	s_waitcnt lgkmcnt(1)
	v_mfma_f32_32x32x16_bf16 v[84:99], v[120:123], v[164:167], v[84:99]
	s_waitcnt lgkmcnt(0)
	v_mfma_f32_32x32x16_bf16 v[68:83], v[124:127], v[164:167], v[68:83]
	s_branch .LBB0_2333

.LBB0_2333:
	v_readlane_b32 s8, v255, 43
	v_readlane_b32 s9, v255, 44
	s_lshl_b64 s[8:9], s[8:9], 23
	s_lshl_b64 s[6:7], s[6:7], 18
	s_lshl_b64 s[8:9], s[8:9], 1
	s_add_u32 s8, s0, s8
	s_addc_u32 s9, s1, s9
	s_lshl_b64 s[6:7], s[6:7], 1
	s_add_u32 s6, s8, s6
	s_addc_u32 s7, s9, s7
	v_lshrrev_b32_e32 v105, 2, v195
	v_lshrrev_b32_e32 v106, 1, v195
	s_lshr_b32 s8, s21, 1
	v_bitop3_b32 v105, s21, v216, v105 bitop3:0xc8
	v_and_b32_e32 v106, 8, v106
	s_and_b32 s8, s8, 4
	v_or3_b32 v105, v106, v105, s8
	s_and_b32 s8, s20, 64
	v_lshlrev_b32_e32 v196, 3, v195
	v_and_b32_e32 v104, 32, v104
	v_and_b32_e32 v197, 24, v196
	s_add_u32 s6, s6, s11
	v_or3_b32 v104, v104, s8, v197
	s_addc_u32 s7, s7, 0
	v_lshlrev_b32_e32 v104, 1, v104
	s_add_u32 s6, s6, 0x7400000
	s_waitcnt vmcnt(4)
	s_mov_b32 m0, s19
	v_lshl_or_b32 v104, v105, 11, v104
	s_addc_u32 s7, s7, 0
	s_waitcnt lgkmcnt(0)
	s_barrier
	v_mov_b32_e32 v105, v3
	v_lshl_add_u64 v[192:193], s[6:7], 0, v[104:105]
	global_load_lds_dwordx4 v104, s[6:7]
	s_mov_b64 s[6:7], 0x10000
	v_lshl_add_u64 v[104:105], v[192:193], 0, s[6:7]
	s_mov_b32 m0, s18
	s_and_b64 vcc, exec, s[4:5]
	global_load_lds_dwordx4 v[104:105], off
	s_cbranch_vccnz .LBB0_2335
	v_xad_u32 v128, v194, v198, v199
	ds_read_b128 v[112:115], v128 offset:16384
	ds_read_b128 v[116:119], v128 offset:24576
	v_xad_u32 v128, v206, v198, v199
	ds_read_b128 v[120:123], v128 offset:16384
	ds_read_b128 v[124:127], v128 offset:24576
	s_waitcnt lgkmcnt(3)
	v_mfma_f32_32x32x16_bf16 v[84:99], v[112:115], v[160:163], v[84:99]
	v_xad_u32 v128, v205, v198, v199
	ds_read_b128 v[112:115], v128 offset:16384
	s_waitcnt lgkmcnt(3)
	v_mfma_f32_32x32x16_bf16 v[68:83], v[116:119], v[160:163], v[68:83]
	ds_read_b128 v[116:119], v128 offset:24576
	s_waitcnt lgkmcnt(3)
	v_mfma_f32_32x32x16_bf16 v[84:99], v[120:123], v[156:159], v[84:99]
	v_xad_u32 v128, v204, v198, v199
	ds_read_b128 v[120:123], v128 offset:16384
	s_waitcnt lgkmcnt(3)
	v_mfma_f32_32x32x16_bf16 v[68:83], v[124:127], v[156:159], v[68:83]
	ds_read_b128 v[124:127], v128 offset:24576
	s_waitcnt lgkmcnt(3)
	v_mfma_f32_32x32x16_bf16 v[84:99], v[112:115], v[152:155], v[84:99]
	v_xad_u32 v128, v203, v198, v199
	ds_read_b128 v[112:115], v128 offset:16384
	s_waitcnt lgkmcnt(3)
	v_mfma_f32_32x32x16_bf16 v[68:83], v[116:119], v[152:155], v[68:83]
	ds_read_b128 v[116:119], v128 offset:24576
	s_waitcnt lgkmcnt(3)
	v_mfma_f32_32x32x16_bf16 v[84:99], v[120:123], v[148:151], v[84:99]
	v_xad_u32 v128, v202, v198, v199
	ds_read_b128 v[120:123], v128 offset:16384
	s_waitcnt lgkmcnt(3)
	v_mfma_f32_32x32x16_bf16 v[68:83], v[124:127], v[148:151], v[68:83]
	ds_read_b128 v[124:127], v128 offset:24576
	s_waitcnt lgkmcnt(3)
	v_mfma_f32_32x32x16_bf16 v[84:99], v[112:115], v[144:147], v[84:99]
	v_xad_u32 v128, v201, v198, v199
	ds_read_b128 v[112:115], v128 offset:16384
	s_waitcnt lgkmcnt(3)
	v_mfma_f32_32x32x16_bf16 v[68:83], v[116:119], v[144:147], v[68:83]
	ds_read_b128 v[116:119], v128 offset:24576
	s_waitcnt lgkmcnt(3)
	v_mfma_f32_32x32x16_bf16 v[84:99], v[120:123], v[140:143], v[84:99]
	v_xad_u32 v128, v200, v198, v199
	ds_read_b128 v[120:123], v128 offset:16384
	s_waitcnt lgkmcnt(3)
	v_mfma_f32_32x32x16_bf16 v[68:83], v[124:127], v[140:143], v[68:83]
	ds_read_b128 v[124:127], v128 offset:24576
	s_waitcnt lgkmcnt(3)
	v_mfma_f32_32x32x16_bf16 v[84:99], v[112:115], v[136:139], v[84:99]
	s_waitcnt lgkmcnt(2)
	v_mfma_f32_32x32x16_bf16 v[68:83], v[116:119], v[136:139], v[68:83]
	s_waitcnt lgkmcnt(1)
	v_mfma_f32_32x32x16_bf16 v[84:99], v[120:123], v[132:135], v[84:99]
	s_waitcnt lgkmcnt(0)
	v_mfma_f32_32x32x16_bf16 v[68:83], v[124:127], v[132:135], v[68:83]
.LBB0_2335:
	s_waitcnt vmcnt(4)
	s_mov_b64 s[6:7], 0x20000
	s_mov_b32 m0, s17
	s_waitcnt lgkmcnt(0)
	s_barrier
	v_lshl_add_u64 v[104:105], v[192:193], 0, s[6:7]
	s_mov_b64 s[6:7], 0x30000
	global_load_lds_dwordx4 v[104:105], off
	v_lshl_add_u64 v[104:105], v[192:193], 0, s[6:7]
	s_mov_b32 m0, s16
	s_and_b64 vcc, exec, s[4:5]
	global_load_lds_dwordx4 v[104:105], off
	s_cbranch_vccnz .LBB0_2337
	v_xad_u32 v236, v194, v198, v199
	ds_read_b128 v[220:223], v236 offset:32768
	v_xad_u32 v236, v206, v198, v199
	ds_read_b128 v[224:227], v236 offset:32768
	v_xad_u32 v236, v194, v198, v199
	ds_read_b128 v[228:231], v236 offset:40960
	v_xad_u32 v236, v206, v198, v199
	ds_read_b128 v[232:235], v236 offset:40960
	s_waitcnt lgkmcnt(3)
	v_mfma_f32_32x32x16_bf16 v[116:131], v[220:223], v[100:103], 0
	v_xad_u32 v236, v205, v198, v199
	ds_read_b128 v[220:223], v236 offset:32768
	s_waitcnt lgkmcnt(3)
	v_mfma_f32_32x32x16_bf16 v[116:131], v[224:227], v[188:191], v[116:131]
	ds_read_b128 v[224:227], v236 offset:40960
	s_waitcnt lgkmcnt(3)
	v_mfma_f32_32x32x16_bf16 v[100:115], v[228:231], v[100:103], 0
	v_xad_u32 v236, v204, v198, v199
	ds_read_b128 v[228:231], v236 offset:32768
	s_waitcnt lgkmcnt(3)
	v_mfma_f32_32x32x16_bf16 v[100:115], v[232:235], v[188:191], v[100:115]
	ds_read_b128 v[232:235], v236 offset:40960
	s_waitcnt lgkmcnt(3)
	v_mfma_f32_32x32x16_bf16 v[116:131], v[220:223], v[184:187], v[116:131]
	v_xad_u32 v236, v203, v198, v199
	ds_read_b128 v[220:223], v236 offset:32768
	s_waitcnt lgkmcnt(3)
	v_mfma_f32_32x32x16_bf16 v[100:115], v[224:227], v[184:187], v[100:115]
	ds_read_b128 v[224:227], v236 offset:40960
	s_waitcnt lgkmcnt(3)
	v_mfma_f32_32x32x16_bf16 v[116:131], v[228:231], v[180:183], v[116:131]
	v_xad_u32 v236, v202, v198, v199
	ds_read_b128 v[228:231], v236 offset:32768
	s_waitcnt lgkmcnt(3)
	v_mfma_f32_32x32x16_bf16 v[100:115], v[232:235], v[180:183], v[100:115]
	ds_read_b128 v[232:235], v236 offset:40960
	s_waitcnt lgkmcnt(3)
	v_mfma_f32_32x32x16_bf16 v[116:131], v[220:223], v[176:179], v[116:131]
	v_xad_u32 v236, v201, v198, v199
	ds_read_b128 v[220:223], v236 offset:32768
	s_waitcnt lgkmcnt(3)
	v_mfma_f32_32x32x16_bf16 v[100:115], v[224:227], v[176:179], v[100:115]
	ds_read_b128 v[224:227], v236 offset:40960
	s_waitcnt lgkmcnt(3)
	v_mfma_f32_32x32x16_bf16 v[116:131], v[228:231], v[172:175], v[116:131]
	v_xad_u32 v236, v200, v198, v199
	ds_read_b128 v[228:231], v236 offset:32768
	s_waitcnt lgkmcnt(3)
	v_mfma_f32_32x32x16_bf16 v[100:115], v[232:235], v[172:175], v[100:115]
	ds_read_b128 v[232:235], v236 offset:40960
	s_waitcnt lgkmcnt(3)
	v_mfma_f32_32x32x16_bf16 v[116:131], v[220:223], v[168:171], v[116:131]
	s_waitcnt lgkmcnt(2)
	v_mfma_f32_32x32x16_bf16 v[100:115], v[224:227], v[168:171], v[100:115]
	s_waitcnt lgkmcnt(1)
	v_mfma_f32_32x32x16_bf16 v[116:131], v[228:231], v[164:167], v[116:131]
	s_waitcnt lgkmcnt(0)
	v_mfma_f32_32x32x16_bf16 v[100:115], v[232:235], v[164:167], v[100:115]
	s_branch .LBB0_2338

.LBB0_2338:
	s_waitcnt vmcnt(4)
	s_mov_b32 m0, s15
	s_waitcnt lgkmcnt(0)
	s_barrier
	v_lshl_add_u64 v[164:165], v[192:193], 0, s[54:55]
	s_mov_b64 s[6:7], 0x50000
	global_load_lds_dwordx4 v[164:165], off
	v_lshl_add_u64 v[164:165], v[192:193], 0, s[6:7]
	s_mov_b32 m0, s14
	s_and_b64 vcc, exec, s[4:5]
	global_load_lds_dwordx4 v[164:165], off
	s_cbranch_vccnz .LBB0_2340
	v_xad_u32 v188, v194, v198, v199
	ds_read_b128 v[172:175], v188 offset:49152
	ds_read_b128 v[176:179], v188 offset:57344
	v_xad_u32 v188, v206, v198, v199
	ds_read_b128 v[180:183], v188 offset:49152
	ds_read_b128 v[184:187], v188 offset:57344
	s_waitcnt lgkmcnt(3)
	v_mfma_f32_32x32x16_bf16 v[116:131], v[172:175], v[160:163], v[116:131]
	v_xad_u32 v188, v205, v198, v199
	ds_read_b128 v[172:175], v188 offset:49152
	s_waitcnt lgkmcnt(3)
	v_mfma_f32_32x32x16_bf16 v[100:115], v[176:179], v[160:163], v[100:115]
	ds_read_b128 v[176:179], v188 offset:57344
	s_waitcnt lgkmcnt(3)
	v_mfma_f32_32x32x16_bf16 v[116:131], v[180:183], v[156:159], v[116:131]
	v_xad_u32 v188, v204, v198, v199
	ds_read_b128 v[180:183], v188 offset:49152
	s_waitcnt lgkmcnt(3)
	v_mfma_f32_32x32x16_bf16 v[100:115], v[184:187], v[156:159], v[100:115]
	ds_read_b128 v[184:187], v188 offset:57344
	s_waitcnt lgkmcnt(3)
	v_mfma_f32_32x32x16_bf16 v[116:131], v[172:175], v[152:155], v[116:131]
	v_xad_u32 v188, v203, v198, v199
	ds_read_b128 v[172:175], v188 offset:49152
	s_waitcnt lgkmcnt(3)
	v_mfma_f32_32x32x16_bf16 v[100:115], v[176:179], v[152:155], v[100:115]
	ds_read_b128 v[176:179], v188 offset:57344
	s_waitcnt lgkmcnt(3)
	v_mfma_f32_32x32x16_bf16 v[116:131], v[180:183], v[148:151], v[116:131]
	v_xad_u32 v188, v202, v198, v199
	ds_read_b128 v[180:183], v188 offset:49152
	s_waitcnt lgkmcnt(3)
	v_mfma_f32_32x32x16_bf16 v[100:115], v[184:187], v[148:151], v[100:115]
	ds_read_b128 v[184:187], v188 offset:57344
	s_waitcnt lgkmcnt(3)
	v_mfma_f32_32x32x16_bf16 v[116:131], v[172:175], v[144:147], v[116:131]
	v_xad_u32 v188, v201, v198, v199
	ds_read_b128 v[172:175], v188 offset:49152
	s_waitcnt lgkmcnt(3)
	v_mfma_f32_32x32x16_bf16 v[100:115], v[176:179], v[144:147], v[100:115]
	ds_read_b128 v[176:179], v188 offset:57344
	s_waitcnt lgkmcnt(3)
	v_mfma_f32_32x32x16_bf16 v[116:131], v[180:183], v[140:143], v[116:131]
	v_xad_u32 v188, v200, v198, v199
	ds_read_b128 v[180:183], v188 offset:49152
	s_waitcnt lgkmcnt(3)
	v_mfma_f32_32x32x16_bf16 v[100:115], v[184:187], v[140:143], v[100:115]
	ds_read_b128 v[184:187], v188 offset:57344
	s_waitcnt lgkmcnt(3)
	v_mfma_f32_32x32x16_bf16 v[116:131], v[172:175], v[136:139], v[116:131]
	s_waitcnt lgkmcnt(2)
	v_mfma_f32_32x32x16_bf16 v[100:115], v[176:179], v[136:139], v[100:115]
	s_waitcnt lgkmcnt(1)
	v_mfma_f32_32x32x16_bf16 v[116:131], v[180:183], v[132:135], v[116:131]
	s_waitcnt lgkmcnt(0)
	v_mfma_f32_32x32x16_bf16 v[100:115], v[184:187], v[132:135], v[100:115]

.LBB0_2527:
	v_add_u32_e32 v166, 0, v126
	s_cmp_gt_u32 s17, 12
	ds_read_b128 v[168:171], v133
	ds_read_b128 v[172:175], v166 offset:18432
	ds_read_b128 v[176:179], v166 offset:20736
	ds_read_b128 v[180:183], v166 offset:23040
	ds_read_b128 v[184:187], v166 offset:25344
	ds_read_b128 v[188:191], v166 offset:27648
	ds_read_b128 v[192:195], v166 offset:29952
	s_waitcnt lgkmcnt(5)
	v_mfma_f32_16x16x32_bf16 v[138:141], v[172:175], v[168:171], v[108:111]
	ds_read_b128 v[172:175], v166 offset:32256
	s_waitcnt lgkmcnt(5)
	v_mfma_f32_16x16x32_bf16 v[112:115], v[176:179], v[168:171], v[112:115]
	ds_read_b128 v[176:179], v166 offset:34560
	s_waitcnt lgkmcnt(5)
	v_mfma_f32_16x16x32_bf16 v[104:107], v[180:183], v[168:171], v[104:107]
	ds_read_b128 v[180:183], v166 offset:36864
	s_waitcnt lgkmcnt(5)
	v_mfma_f32_16x16x32_bf16 v[142:145], v[184:187], v[168:171], v[100:103]
	ds_read_b128 v[184:187], v166 offset:39168
	s_waitcnt lgkmcnt(5)
	v_mfma_f32_16x16x32_bf16 v[96:99], v[188:191], v[168:171], v[96:99]
	ds_read_b128 v[188:191], v166 offset:41472
	s_waitcnt lgkmcnt(5)
	v_mfma_f32_16x16x32_bf16 v[146:149], v[192:195], v[168:171], v[92:95]
	ds_read_b128 v[192:195], v166 offset:43776
	s_waitcnt lgkmcnt(5)
	v_mfma_f32_16x16x32_bf16 v[88:91], v[172:175], v[168:171], v[88:91]
	ds_read_b128 v[172:175], v166 offset:46080
	s_waitcnt lgkmcnt(5)
	v_mfma_f32_16x16x32_bf16 v[150:153], v[176:179], v[168:171], v[84:87]
	ds_read_b128 v[176:179], v166 offset:48384
	s_waitcnt lgkmcnt(5)
	v_mfma_f32_16x16x32_bf16 v[154:157], v[180:183], v[168:171], v[80:83]
	ds_read_b128 v[180:183], v166 offset:50688
	s_waitcnt lgkmcnt(5)
	v_mfma_f32_16x16x32_bf16 v[158:161], v[184:187], v[168:171], v[76:79]
	ds_read_b128 v[184:187], v166 offset:52992
	s_waitcnt lgkmcnt(5)
	v_mfma_f32_16x16x32_bf16 v[162:165], v[188:191], v[168:171], v[72:75]
	ds_read_b128 v[134:137], v133 offset:64
	s_waitcnt lgkmcnt(5)
	v_mfma_f32_16x16x32_bf16 v[108:111], v[192:195], v[168:171], v[68:71]
	ds_read_b128 v[188:191], v166 offset:18496
	s_waitcnt lgkmcnt(5)
	v_mfma_f32_16x16x32_bf16 v[100:103], v[172:175], v[168:171], v[64:67]
	ds_read_b128 v[172:175], v166 offset:20800
	s_waitcnt lgkmcnt(5)
	v_mfma_f32_16x16x32_bf16 v[92:95], v[176:179], v[168:171], v[60:63]
	ds_read_b128 v[176:179], v166 offset:23104
	s_waitcnt lgkmcnt(5)
	v_mfma_f32_16x16x32_bf16 v[84:87], v[180:183], v[168:171], v[56:59]
	ds_read_b128 v[64:67], v166 offset:25408
	s_waitcnt lgkmcnt(5)
	v_mfma_f32_16x16x32_bf16 v[76:79], v[184:187], v[168:171], v[52:55]
	ds_read_b128 v[168:171], v166 offset:43840
	ds_read_b128 v[180:183], v166 offset:27712
	s_waitcnt lgkmcnt(5)
	v_mfma_f32_16x16x32_bf16 v[52:55], v[188:191], v[134:137], v[138:141]
	ds_read_b128 v[184:187], v166 offset:46144
	ds_read_b128 v[188:191], v166 offset:32320
	ds_read_b128 v[72:75], v166 offset:30016
	ds_read_b128 v[192:195], v166 offset:48448
	s_waitcnt lgkmcnt(5)
	v_mfma_f32_16x16x32_bf16 v[108:111], v[168:171], v[134:137], v[108:111]
	ds_read_b128 v[168:171], v166 offset:50752
	s_waitcnt lgkmcnt(4)
	v_mfma_f32_16x16x32_bf16 v[100:103], v[184:187], v[134:137], v[100:103]
	s_waitcnt lgkmcnt(1)
	v_mfma_f32_16x16x32_bf16 v[92:95], v[192:195], v[134:137], v[92:95]
	s_waitcnt lgkmcnt(9)
	v_mfma_f32_16x16x32_bf16 v[56:59], v[172:175], v[134:137], v[112:115]
	s_waitcnt lgkmcnt(8)
	v_mfma_f32_16x16x32_bf16 v[60:63], v[176:179], v[134:137], v[104:107]
	s_waitcnt lgkmcnt(5)
	v_mfma_f32_16x16x32_bf16 v[68:71], v[180:183], v[134:137], v[96:99]
	ds_read_b128 v[112:115], v166 offset:41536
	ds_read_b128 v[104:107], v166 offset:39232
	s_waitcnt lgkmcnt(5)
	v_mfma_f32_16x16x32_bf16 v[80:83], v[188:191], v[134:137], v[88:91]
	ds_read_b128 v[96:99], v166 offset:36928
	s_nop 2
	ds_read_b128 v[88:91], v166 offset:34624
	s_waitcnt lgkmcnt(4)
	v_mfma_f32_16x16x32_bf16 v[84:87], v[168:171], v[134:137], v[84:87]
	s_waitcnt lgkmcnt(4)
	ds_read_b128 v[138:141], v166 offset:53056
	s_waitcnt vmcnt(4)
	ds_write_b128 v128, v[28:31] offset:55296
	s_waitcnt vmcnt(3)
	ds_write_b128 v128, v[32:35] offset:64512
	ds_write_b128 v129, v[36:39]
	s_waitcnt vmcnt(2)
	ds_write_b128 v130, v[40:43]
	s_waitcnt vmcnt(1)
	ds_write_b128 v131, v[44:47]
	s_waitcnt vmcnt(0)
	ds_write_b128 v132, v[48:51]
	s_waitcnt lgkmcnt(0)
	v_mfma_f32_16x16x32_bf16 v[64:67], v[64:67], v[134:137], v[142:145]
	s_barrier
	v_mfma_f32_16x16x32_bf16 v[72:75], v[72:75], v[134:137], v[146:149]
	s_waitcnt lgkmcnt(7)
	v_mfma_f32_16x16x32_bf16 v[88:91], v[88:91], v[134:137], v[150:153]
	v_mfma_f32_16x16x32_bf16 v[96:99], v[96:99], v[134:137], v[154:157]
	v_mfma_f32_16x16x32_bf16 v[104:107], v[104:107], v[134:137], v[158:161]
	v_mfma_f32_16x16x32_bf16 v[112:115], v[112:115], v[134:137], v[162:165]
	s_waitcnt lgkmcnt(6)
	v_mfma_f32_16x16x32_bf16 v[76:79], v[138:141], v[134:137], v[76:79]
	s_cbranch_scc1 .LBB0_2529
	v_add_co_u32_e32 v28, vcc, 0x11400000, v124
	s_nop 1
	v_addc_co_u32_e32 v29, vcc, 0, v125, vcc
	v_add_co_u32_e32 v32, vcc, 0x11420000, v124
	s_nop 1
	v_addc_co_u32_e32 v33, vcc, 0, v125, vcc
	v_add_co_u32_e32 v36, vcc, 0xe00000, v122
	global_load_dwordx4 v[28:31], v[28:29], off offset:384
	s_nop 0
	global_load_dwordx4 v[32:35], v[32:33], off offset:384
	v_addc_co_u32_e32 v37, vcc, 0, v123, vcc
	v_add_co_u32_e32 v40, vcc, 0xe20000, v122
	s_nop 1
	v_addc_co_u32_e32 v41, vcc, 0, v123, vcc
	v_add_co_u32_e32 v44, vcc, 0xe40000, v122
	global_load_dwordx4 v[36:39], v[36:37], off offset:384
	s_nop 0
	global_load_dwordx4 v[40:43], v[40:41], off offset:384
	v_addc_co_u32_e32 v45, vcc, 0, v123, vcc
	v_add_co_u32_e32 v48, vcc, 0xe60000, v122
	s_nop 1
	v_addc_co_u32_e32 v49, vcc, 0, v123, vcc
	global_load_dwordx4 v[44:47], v[44:45], off offset:384
	s_nop 0
	global_load_dwordx4 v[48:51], v[48:49], off offset:384
.LBB0_2529:
	v_add_u32_e32 v170, 0, v127
	s_add_i32 s18, 0, 0xd800
	v_add_u32_e32 v171, s18, v127
	s_andn2_b64 vcc, exec, s[12:13]
	ds_read_b128 v[172:175], v133 offset:55296
	ds_read_b128 v[176:179], v170 offset:55296
	ds_read_b128 v[180:183], v170 offset:57600
	ds_read_b128 v[184:187], v170 offset:59904
	ds_read_b128 v[188:191], v170 offset:62208
	ds_read_b128 v[192:195], v170 offset:64512
	ds_read_b128 v[196:199], v171 offset:11520
	s_waitcnt lgkmcnt(5)
	v_mfma_f32_16x16x32_bf16 v[134:137], v[176:179], v[172:175], v[52:55]
	ds_read_b128 v[176:179], v171 offset:13824
	s_waitcnt lgkmcnt(5)
	v_mfma_f32_16x16x32_bf16 v[138:141], v[180:183], v[172:175], v[56:59]
	ds_read_b128 v[180:183], v171 offset:16128
	s_waitcnt lgkmcnt(5)
	v_mfma_f32_16x16x32_bf16 v[142:145], v[184:187], v[172:175], v[60:63]
	ds_read_b128 v[184:187], v171 offset:18432
	s_waitcnt lgkmcnt(5)
	v_mfma_f32_16x16x32_bf16 v[146:149], v[188:191], v[172:175], v[64:67]
	ds_read_b128 v[188:191], v171 offset:20736
	s_waitcnt lgkmcnt(5)
	v_mfma_f32_16x16x32_bf16 v[150:153], v[192:195], v[172:175], v[68:71]
	ds_read_b128 v[192:195], v171 offset:23040
	s_waitcnt lgkmcnt(5)
	v_mfma_f32_16x16x32_bf16 v[154:157], v[196:199], v[172:175], v[72:75]
	ds_read_b128 v[196:199], v171 offset:25344
	s_waitcnt lgkmcnt(5)
	v_mfma_f32_16x16x32_bf16 v[80:83], v[176:179], v[172:175], v[80:83]
	ds_read_b128 v[176:179], v171 offset:27648
	s_waitcnt lgkmcnt(5)
	v_mfma_f32_16x16x32_bf16 v[158:161], v[180:183], v[172:175], v[88:91]
	ds_read_b128 v[180:183], v171 offset:29952
	s_waitcnt lgkmcnt(5)
	v_mfma_f32_16x16x32_bf16 v[162:165], v[184:187], v[172:175], v[96:99]
	ds_read_b128 v[184:187], v171 offset:32256
	s_waitcnt lgkmcnt(5)
	v_mfma_f32_16x16x32_bf16 v[166:169], v[188:191], v[172:175], v[104:107]
	ds_read_b128 v[188:191], v171 offset:34560
	s_waitcnt lgkmcnt(5)
	v_mfma_f32_16x16x32_bf16 v[72:75], v[192:195], v[172:175], v[112:115]
	ds_read_b128 v[192:195], v133 offset:55360
	s_waitcnt lgkmcnt(5)
	v_mfma_f32_16x16x32_bf16 v[68:71], v[196:199], v[172:175], v[108:111]
	ds_read_b128 v[196:199], v170 offset:55360
	s_waitcnt lgkmcnt(5)
	v_mfma_f32_16x16x32_bf16 v[64:67], v[176:179], v[172:175], v[100:103]
	ds_read_b128 v[176:179], v170 offset:57664
	s_waitcnt lgkmcnt(5)
	v_mfma_f32_16x16x32_bf16 v[60:63], v[180:183], v[172:175], v[92:95]
	ds_read_b128 v[180:183], v171 offset:23104
	s_waitcnt lgkmcnt(5)
	v_mfma_f32_16x16x32_bf16 v[56:59], v[184:187], v[172:175], v[84:87]
	ds_read_b128 v[184:187], v171 offset:25408
	s_waitcnt lgkmcnt(5)
	v_mfma_f32_16x16x32_bf16 v[52:55], v[188:191], v[172:175], v[76:79]
	ds_read_b128 v[172:175], v171 offset:27712
	ds_read_b128 v[188:191], v171 offset:30016
	s_waitcnt lgkmcnt(5)
	v_mfma_f32_16x16x32_bf16 v[108:111], v[196:199], v[192:195], v[134:137]
	ds_read_b128 v[196:199], v171 offset:32320
	ds_read_b128 v[200:203], v171 offset:34624
	s_waitcnt lgkmcnt(5)
	v_mfma_f32_16x16x32_bf16 v[72:75], v[180:183], v[192:195], v[72:75]
	ds_read_b128 v[180:183], v170 offset:59968
	s_waitcnt lgkmcnt(5)
	v_mfma_f32_16x16x32_bf16 v[68:71], v[184:187], v[192:195], v[68:71]
	ds_read_b128 v[184:187], v170 offset:62272
	s_waitcnt lgkmcnt(5)
	v_mfma_f32_16x16x32_bf16 v[64:67], v[172:175], v[192:195], v[64:67]
	ds_read_b128 v[172:175], v170 offset:64576
	s_waitcnt lgkmcnt(5)
	v_mfma_f32_16x16x32_bf16 v[60:63], v[188:191], v[192:195], v[60:63]
	ds_read_b128 v[188:191], v171 offset:11584
	s_waitcnt lgkmcnt(5)
	v_mfma_f32_16x16x32_bf16 v[56:59], v[196:199], v[192:195], v[56:59]
	s_waitcnt lgkmcnt(10)
	v_mfma_f32_16x16x32_bf16 v[112:115], v[176:179], v[192:195], v[138:141]
	ds_read_b128 v[176:179], v171 offset:13888
	ds_read_b128 v[196:199], v171 offset:16192
	s_waitcnt lgkmcnt(5)
	v_mfma_f32_16x16x32_bf16 v[104:107], v[180:183], v[192:195], v[142:145]
	ds_read_b128 v[180:183], v171 offset:18496
	s_waitcnt lgkmcnt(5)
	v_mfma_f32_16x16x32_bf16 v[100:103], v[184:187], v[192:195], v[146:149]
	ds_read_b128 v[184:187], v171 offset:20800
	s_waitcnt lgkmcnt(5)
	v_mfma_f32_16x16x32_bf16 v[96:99], v[172:175], v[192:195], v[150:153]
	s_waitcnt lgkmcnt(4)
	v_mfma_f32_16x16x32_bf16 v[92:95], v[188:191], v[192:195], v[154:157]
	s_waitcnt lgkmcnt(3)
	v_mfma_f32_16x16x32_bf16 v[88:91], v[176:179], v[192:195], v[80:83]
	s_waitcnt lgkmcnt(2)
	v_mfma_f32_16x16x32_bf16 v[84:87], v[196:199], v[192:195], v[158:161]
	s_waitcnt lgkmcnt(1)
	v_mfma_f32_16x16x32_bf16 v[80:83], v[180:183], v[192:195], v[162:165]
	s_waitcnt lgkmcnt(0)
	v_mfma_f32_16x16x32_bf16 v[76:79], v[184:187], v[192:195], v[166:169]
	s_waitcnt lgkmcnt(8)
	v_mfma_f32_16x16x32_bf16 v[52:55], v[200:203], v[192:195], v[52:55]
	s_waitcnt lgkmcnt(0)
	s_cbranch_vccnz .LBB0_2524
	ds_write_b128 v128, v[4:7]
	ds_write_b128 v128, v[8:11] offset:9216
	ds_write_b128 v128, v[12:15] offset:18432
	ds_write_b128 v128, v[16:19] offset:27648
	ds_write_b128 v128, v[20:23] offset:36864
	ds_write_b128 v128, v[24:27] offset:46080
	s_branch .LBB0_2524

.LBB0_2551:
	v_add_u32_e32 v166, 0, v126
	s_cmp_gt_u32 s9, 12
	ds_read_b128 v[168:171], v133
	ds_read_b128 v[172:175], v166 offset:18432
	ds_read_b128 v[176:179], v166 offset:20736
	ds_read_b128 v[180:183], v166 offset:23040
	ds_read_b128 v[184:187], v166 offset:25344
	ds_read_b128 v[188:191], v166 offset:27648
	ds_read_b128 v[192:195], v166 offset:29952
	s_waitcnt lgkmcnt(5)
	v_mfma_f32_16x16x32_bf16 v[138:141], v[172:175], v[168:171], v[108:111]
	ds_read_b128 v[172:175], v166 offset:32256
	s_waitcnt lgkmcnt(5)
	v_mfma_f32_16x16x32_bf16 v[112:115], v[176:179], v[168:171], v[112:115]
	ds_read_b128 v[176:179], v166 offset:34560
	s_waitcnt lgkmcnt(5)
	v_mfma_f32_16x16x32_bf16 v[104:107], v[180:183], v[168:171], v[104:107]
	ds_read_b128 v[180:183], v166 offset:36864
	s_waitcnt lgkmcnt(5)
	v_mfma_f32_16x16x32_bf16 v[142:145], v[184:187], v[168:171], v[100:103]
	ds_read_b128 v[184:187], v166 offset:39168
	s_waitcnt lgkmcnt(5)
	v_mfma_f32_16x16x32_bf16 v[96:99], v[188:191], v[168:171], v[96:99]
	ds_read_b128 v[188:191], v166 offset:41472
	s_waitcnt lgkmcnt(5)
	v_mfma_f32_16x16x32_bf16 v[146:149], v[192:195], v[168:171], v[92:95]
	ds_read_b128 v[192:195], v166 offset:43776
	s_waitcnt lgkmcnt(5)
	v_mfma_f32_16x16x32_bf16 v[88:91], v[172:175], v[168:171], v[88:91]
	ds_read_b128 v[172:175], v166 offset:46080
	s_waitcnt lgkmcnt(5)
	v_mfma_f32_16x16x32_bf16 v[150:153], v[176:179], v[168:171], v[84:87]
	ds_read_b128 v[176:179], v166 offset:48384
	s_waitcnt lgkmcnt(5)
	v_mfma_f32_16x16x32_bf16 v[154:157], v[180:183], v[168:171], v[80:83]
	ds_read_b128 v[180:183], v166 offset:50688
	s_waitcnt lgkmcnt(5)
	v_mfma_f32_16x16x32_bf16 v[158:161], v[184:187], v[168:171], v[76:79]
	ds_read_b128 v[184:187], v166 offset:52992
	s_waitcnt lgkmcnt(5)
	v_mfma_f32_16x16x32_bf16 v[162:165], v[188:191], v[168:171], v[72:75]
	ds_read_b128 v[134:137], v133 offset:64
	s_waitcnt lgkmcnt(5)
	v_mfma_f32_16x16x32_bf16 v[108:111], v[192:195], v[168:171], v[68:71]
	ds_read_b128 v[188:191], v166 offset:18496
	s_waitcnt lgkmcnt(5)
	v_mfma_f32_16x16x32_bf16 v[100:103], v[172:175], v[168:171], v[64:67]
	ds_read_b128 v[172:175], v166 offset:20800
	s_waitcnt lgkmcnt(5)
	v_mfma_f32_16x16x32_bf16 v[92:95], v[176:179], v[168:171], v[60:63]
	ds_read_b128 v[176:179], v166 offset:23104
	s_waitcnt lgkmcnt(5)
	v_mfma_f32_16x16x32_bf16 v[84:87], v[180:183], v[168:171], v[56:59]
	ds_read_b128 v[64:67], v166 offset:25408
	s_waitcnt lgkmcnt(5)
	v_mfma_f32_16x16x32_bf16 v[76:79], v[184:187], v[168:171], v[52:55]
	ds_read_b128 v[168:171], v166 offset:43840
	ds_read_b128 v[180:183], v166 offset:27712
	s_waitcnt lgkmcnt(5)
	v_mfma_f32_16x16x32_bf16 v[52:55], v[188:191], v[134:137], v[138:141]
	ds_read_b128 v[184:187], v166 offset:46144
	ds_read_b128 v[188:191], v166 offset:32320
	ds_read_b128 v[72:75], v166 offset:30016
	ds_read_b128 v[192:195], v166 offset:48448
	s_waitcnt lgkmcnt(5)
	v_mfma_f32_16x16x32_bf16 v[108:111], v[168:171], v[134:137], v[108:111]
	ds_read_b128 v[168:171], v166 offset:50752
	s_waitcnt lgkmcnt(4)
	v_mfma_f32_16x16x32_bf16 v[100:103], v[184:187], v[134:137], v[100:103]
	s_waitcnt lgkmcnt(1)
	v_mfma_f32_16x16x32_bf16 v[92:95], v[192:195], v[134:137], v[92:95]
	s_waitcnt lgkmcnt(9)
	v_mfma_f32_16x16x32_bf16 v[56:59], v[172:175], v[134:137], v[112:115]
	s_waitcnt lgkmcnt(8)
	v_mfma_f32_16x16x32_bf16 v[60:63], v[176:179], v[134:137], v[104:107]
	s_waitcnt lgkmcnt(5)
	v_mfma_f32_16x16x32_bf16 v[68:71], v[180:183], v[134:137], v[96:99]
	ds_read_b128 v[112:115], v166 offset:41536
	ds_read_b128 v[104:107], v166 offset:39232
	s_waitcnt lgkmcnt(5)
	v_mfma_f32_16x16x32_bf16 v[80:83], v[188:191], v[134:137], v[88:91]
	ds_read_b128 v[96:99], v166 offset:36928
	s_nop 2
	ds_read_b128 v[88:91], v166 offset:34624
	s_waitcnt lgkmcnt(4)
	v_mfma_f32_16x16x32_bf16 v[84:87], v[168:171], v[134:137], v[84:87]
	s_waitcnt lgkmcnt(4)
	ds_read_b128 v[138:141], v166 offset:53056
	s_waitcnt vmcnt(4)
	ds_write_b128 v128, v[28:31] offset:55296
	s_waitcnt vmcnt(3)
	ds_write_b128 v128, v[32:35] offset:64512
	ds_write_b128 v129, v[36:39]
	s_waitcnt vmcnt(2)
	ds_write_b128 v130, v[40:43]
	s_waitcnt vmcnt(1)
	ds_write_b128 v131, v[44:47]
	s_waitcnt vmcnt(0)
	ds_write_b128 v132, v[48:51]
	s_waitcnt lgkmcnt(0)
	v_mfma_f32_16x16x32_bf16 v[64:67], v[64:67], v[134:137], v[142:145]
	s_barrier
	v_mfma_f32_16x16x32_bf16 v[72:75], v[72:75], v[134:137], v[146:149]
	s_waitcnt lgkmcnt(7)
	v_mfma_f32_16x16x32_bf16 v[88:91], v[88:91], v[134:137], v[150:153]
	v_mfma_f32_16x16x32_bf16 v[96:99], v[96:99], v[134:137], v[154:157]
	v_mfma_f32_16x16x32_bf16 v[104:107], v[104:107], v[134:137], v[158:161]
	v_mfma_f32_16x16x32_bf16 v[112:115], v[112:115], v[134:137], v[162:165]
	s_waitcnt lgkmcnt(6)
	v_mfma_f32_16x16x32_bf16 v[76:79], v[138:141], v[134:137], v[76:79]
	s_cbranch_scc1 .LBB0_2553
	v_add_co_u32_e32 v28, vcc, 0x11400000, v124
	s_nop 1
	v_addc_co_u32_e32 v29, vcc, 0, v125, vcc
	v_add_co_u32_e32 v32, vcc, 0x11420000, v124
	s_nop 1
	v_addc_co_u32_e32 v33, vcc, 0, v125, vcc
	v_add_co_u32_e32 v36, vcc, 0xe00000, v122
	global_load_dwordx4 v[28:31], v[28:29], off offset:384
	s_nop 0
	global_load_dwordx4 v[32:35], v[32:33], off offset:384
	v_addc_co_u32_e32 v37, vcc, 0, v123, vcc
	v_add_co_u32_e32 v40, vcc, 0xe20000, v122
	s_nop 1
	v_addc_co_u32_e32 v41, vcc, 0, v123, vcc
	v_add_co_u32_e32 v44, vcc, 0xe40000, v122
	global_load_dwordx4 v[36:39], v[36:37], off offset:384
	s_nop 0
	global_load_dwordx4 v[40:43], v[40:41], off offset:384
	v_addc_co_u32_e32 v45, vcc, 0, v123, vcc
	v_add_co_u32_e32 v48, vcc, 0xe60000, v122
	s_nop 1
	v_addc_co_u32_e32 v49, vcc, 0, v123, vcc
	global_load_dwordx4 v[44:47], v[44:45], off offset:384
	s_nop 0
	global_load_dwordx4 v[48:51], v[48:49], off offset:384
.LBB0_2553:
	v_add_u32_e32 v170, 0, v127
	s_add_i32 s12, 0, 0xd800
	v_add_u32_e32 v171, s12, v127
	s_andn2_b64 vcc, exec, s[6:7]
	ds_read_b128 v[172:175], v133 offset:55296
	ds_read_b128 v[176:179], v170 offset:55296
	ds_read_b128 v[180:183], v170 offset:57600
	ds_read_b128 v[184:187], v170 offset:59904
	ds_read_b128 v[188:191], v170 offset:62208
	ds_read_b128 v[192:195], v170 offset:64512
	ds_read_b128 v[196:199], v171 offset:11520
	s_waitcnt lgkmcnt(5)
	v_mfma_f32_16x16x32_bf16 v[134:137], v[176:179], v[172:175], v[52:55]
	ds_read_b128 v[176:179], v171 offset:13824
	s_waitcnt lgkmcnt(5)
	v_mfma_f32_16x16x32_bf16 v[138:141], v[180:183], v[172:175], v[56:59]
	ds_read_b128 v[180:183], v171 offset:16128
	s_waitcnt lgkmcnt(5)
	v_mfma_f32_16x16x32_bf16 v[142:145], v[184:187], v[172:175], v[60:63]
	ds_read_b128 v[184:187], v171 offset:18432
	s_waitcnt lgkmcnt(5)
	v_mfma_f32_16x16x32_bf16 v[146:149], v[188:191], v[172:175], v[64:67]
	ds_read_b128 v[188:191], v171 offset:20736
	s_waitcnt lgkmcnt(5)
	v_mfma_f32_16x16x32_bf16 v[150:153], v[192:195], v[172:175], v[68:71]
	ds_read_b128 v[192:195], v171 offset:23040
	s_waitcnt lgkmcnt(5)
	v_mfma_f32_16x16x32_bf16 v[154:157], v[196:199], v[172:175], v[72:75]
	ds_read_b128 v[196:199], v171 offset:25344
	s_waitcnt lgkmcnt(5)
	v_mfma_f32_16x16x32_bf16 v[80:83], v[176:179], v[172:175], v[80:83]
	ds_read_b128 v[176:179], v171 offset:27648
	s_waitcnt lgkmcnt(5)
	v_mfma_f32_16x16x32_bf16 v[158:161], v[180:183], v[172:175], v[88:91]
	ds_read_b128 v[180:183], v171 offset:29952
	s_waitcnt lgkmcnt(5)
	v_mfma_f32_16x16x32_bf16 v[162:165], v[184:187], v[172:175], v[96:99]
	ds_read_b128 v[184:187], v171 offset:32256
	s_waitcnt lgkmcnt(5)
	v_mfma_f32_16x16x32_bf16 v[166:169], v[188:191], v[172:175], v[104:107]
	ds_read_b128 v[188:191], v171 offset:34560
	s_waitcnt lgkmcnt(5)
	v_mfma_f32_16x16x32_bf16 v[72:75], v[192:195], v[172:175], v[112:115]
	ds_read_b128 v[192:195], v133 offset:55360
	s_waitcnt lgkmcnt(5)
	v_mfma_f32_16x16x32_bf16 v[68:71], v[196:199], v[172:175], v[108:111]
	ds_read_b128 v[196:199], v170 offset:55360
	s_waitcnt lgkmcnt(5)
	v_mfma_f32_16x16x32_bf16 v[64:67], v[176:179], v[172:175], v[100:103]
	ds_read_b128 v[176:179], v170 offset:57664
	s_waitcnt lgkmcnt(5)
	v_mfma_f32_16x16x32_bf16 v[60:63], v[180:183], v[172:175], v[92:95]
	ds_read_b128 v[180:183], v171 offset:23104
	s_waitcnt lgkmcnt(5)
	v_mfma_f32_16x16x32_bf16 v[56:59], v[184:187], v[172:175], v[84:87]
	ds_read_b128 v[184:187], v171 offset:25408
	s_waitcnt lgkmcnt(5)
	v_mfma_f32_16x16x32_bf16 v[52:55], v[188:191], v[172:175], v[76:79]
	ds_read_b128 v[172:175], v171 offset:27712
	ds_read_b128 v[188:191], v171 offset:30016
	s_waitcnt lgkmcnt(5)
	v_mfma_f32_16x16x32_bf16 v[108:111], v[196:199], v[192:195], v[134:137]
	ds_read_b128 v[196:199], v171 offset:32320
	ds_read_b128 v[200:203], v171 offset:34624
	s_waitcnt lgkmcnt(5)
	v_mfma_f32_16x16x32_bf16 v[72:75], v[180:183], v[192:195], v[72:75]
	ds_read_b128 v[180:183], v170 offset:59968
	s_waitcnt lgkmcnt(5)
	v_mfma_f32_16x16x32_bf16 v[68:71], v[184:187], v[192:195], v[68:71]
	ds_read_b128 v[184:187], v170 offset:62272
	s_waitcnt lgkmcnt(5)
	v_mfma_f32_16x16x32_bf16 v[64:67], v[172:175], v[192:195], v[64:67]
	ds_read_b128 v[172:175], v170 offset:64576
	s_waitcnt lgkmcnt(5)
	v_mfma_f32_16x16x32_bf16 v[60:63], v[188:191], v[192:195], v[60:63]
	ds_read_b128 v[188:191], v171 offset:11584
	s_waitcnt lgkmcnt(5)
	v_mfma_f32_16x16x32_bf16 v[56:59], v[196:199], v[192:195], v[56:59]
	s_waitcnt lgkmcnt(10)
	v_mfma_f32_16x16x32_bf16 v[112:115], v[176:179], v[192:195], v[138:141]
	ds_read_b128 v[176:179], v171 offset:13888
	ds_read_b128 v[196:199], v171 offset:16192
	s_waitcnt lgkmcnt(5)
	v_mfma_f32_16x16x32_bf16 v[104:107], v[180:183], v[192:195], v[142:145]
	ds_read_b128 v[180:183], v171 offset:18496
	s_waitcnt lgkmcnt(5)
	v_mfma_f32_16x16x32_bf16 v[100:103], v[184:187], v[192:195], v[146:149]
	ds_read_b128 v[184:187], v171 offset:20800
	s_waitcnt lgkmcnt(5)
	v_mfma_f32_16x16x32_bf16 v[96:99], v[172:175], v[192:195], v[150:153]
	s_waitcnt lgkmcnt(4)
	v_mfma_f32_16x16x32_bf16 v[92:95], v[188:191], v[192:195], v[154:157]
	s_waitcnt lgkmcnt(3)
	v_mfma_f32_16x16x32_bf16 v[88:91], v[176:179], v[192:195], v[80:83]
	s_waitcnt lgkmcnt(2)
	v_mfma_f32_16x16x32_bf16 v[84:87], v[196:199], v[192:195], v[158:161]
	s_waitcnt lgkmcnt(1)
	v_mfma_f32_16x16x32_bf16 v[80:83], v[180:183], v[192:195], v[162:165]
	s_waitcnt lgkmcnt(0)
	v_mfma_f32_16x16x32_bf16 v[76:79], v[184:187], v[192:195], v[166:169]
	s_waitcnt lgkmcnt(8)
	v_mfma_f32_16x16x32_bf16 v[52:55], v[200:203], v[192:195], v[52:55]
	s_waitcnt lgkmcnt(0)
	s_cbranch_vccnz .LBB0_2548
	ds_write_b128 v128, v[4:7]
	ds_write_b128 v128, v[8:11] offset:9216
	ds_write_b128 v128, v[12:15] offset:18432
	ds_write_b128 v128, v[16:19] offset:27648
	ds_write_b128 v128, v[20:23] offset:36864
	ds_write_b128 v128, v[24:27] offset:46080
	s_branch .LBB0_2548

.LBB0_2632:
	v_add_u32_e32 v94, 0, v79
	s_cmp_gt_u32 s17, 28
	ds_read_b128 v[96:99], v85
	ds_read_b128 v[100:103], v94 offset:34816
	ds_read_b128 v[104:107], v94 offset:39168
	ds_read_b128 v[108:111], v94 offset:43520
	ds_read_b128 v[112:115], v94 offset:47872
	ds_read_b128 v[116:119], v85 offset:64
	ds_read_b128 v[120:123], v94 offset:34880
	s_waitcnt lgkmcnt(5)
	v_mfma_f32_16x16x32_bf16 v[52:55], v[100:103], v[96:99], v[52:55]
	ds_read_b128 v[100:103], v94 offset:39232
	s_waitcnt lgkmcnt(5)
	v_mfma_f32_16x16x32_bf16 v[64:67], v[104:107], v[96:99], v[64:67]
	ds_read_b128 v[104:107], v94 offset:43584
	s_waitcnt lgkmcnt(5)
	v_mfma_f32_16x16x32_bf16 v[60:63], v[108:111], v[96:99], v[60:63]
	ds_read_b128 v[108:111], v94 offset:47936
	s_waitcnt lgkmcnt(5)
	v_mfma_f32_16x16x32_bf16 v[56:59], v[112:115], v[96:99], v[56:59]
	ds_read_b128 v[96:99], v85 offset:128
	ds_read_b128 v[112:115], v94 offset:34944
	s_waitcnt lgkmcnt(5)
	v_mfma_f32_16x16x32_bf16 v[52:55], v[120:123], v[116:119], v[52:55]
	ds_read_b128 v[120:123], v94 offset:39296
	s_waitcnt lgkmcnt(5)
	v_mfma_f32_16x16x32_bf16 v[64:67], v[100:103], v[116:119], v[64:67]
	ds_read_b128 v[100:103], v94 offset:43648
	s_waitcnt lgkmcnt(5)
	v_mfma_f32_16x16x32_bf16 v[60:63], v[104:107], v[116:119], v[60:63]
	ds_read_b128 v[104:107], v94 offset:48000
	s_waitcnt lgkmcnt(5)
	v_mfma_f32_16x16x32_bf16 v[56:59], v[108:111], v[116:119], v[56:59]
	ds_read_b128 v[90:93], v85 offset:192
	ds_read_b128 v[108:111], v94 offset:35008
	s_waitcnt lgkmcnt(5)
	v_mfma_f32_16x16x32_bf16 v[52:55], v[112:115], v[96:99], v[52:55]
	ds_read_b128 v[112:115], v94 offset:39360
	s_waitcnt lgkmcnt(5)
	v_mfma_f32_16x16x32_bf16 v[64:67], v[120:123], v[96:99], v[64:67]
	ds_read_b128 v[116:119], v94 offset:43712
	s_waitcnt lgkmcnt(5)
	v_mfma_f32_16x16x32_bf16 v[60:63], v[100:103], v[96:99], v[60:63]
	s_waitcnt lgkmcnt(4)
	v_mfma_f32_16x16x32_bf16 v[86:89], v[104:107], v[96:99], v[56:59]
	s_waitcnt lgkmcnt(2)
	v_mfma_f32_16x16x32_bf16 v[52:55], v[108:111], v[90:93], v[52:55]
	s_waitcnt lgkmcnt(1)
	v_mfma_f32_16x16x32_bf16 v[56:59], v[112:115], v[90:93], v[64:67]
	s_waitcnt lgkmcnt(0)
	v_mfma_f32_16x16x32_bf16 v[60:63], v[116:119], v[90:93], v[60:63]
	s_waitcnt lgkmcnt(0)
	ds_read_b128 v[64:67], v94 offset:48064
	s_waitcnt vmcnt(5)
	ds_write_b128 v80, v[12:15] offset:52224
	s_waitcnt vmcnt(4)
	ds_write_b128 v80, v[16:19] offset:60928
	s_waitcnt vmcnt(3)
	ds_write_b128 v81, v[28:31] offset:17408
	s_waitcnt vmcnt(2)
	ds_write_b128 v81, v[32:35] offset:26112
	s_waitcnt vmcnt(1)
	ds_write_b128 v82, v[44:47]
	s_waitcnt vmcnt(0)
	ds_write_b128 v83, v[48:51]
	s_waitcnt lgkmcnt(0)
	s_waitcnt lgkmcnt(6)
	v_mfma_f32_16x16x32_bf16 v[64:67], v[64:67], v[90:93], v[86:89]
	s_barrier
	s_cbranch_scc1 .LBB0_2634
	v_add_co_u32_e32 v12, vcc, 0x31800000, v76
	s_nop 1
	v_addc_co_u32_e32 v13, vcc, 0, v77, vcc
	v_add_co_u32_e32 v16, vcc, 0x31840000, v76
	s_nop 1
	v_addc_co_u32_e32 v17, vcc, 0, v77, vcc
	v_add_co_u32_e32 v28, vcc, 0x31880000, v76
	global_load_dwordx4 v[12:15], v[12:13], off offset:768
	s_nop 0
	global_load_dwordx4 v[16:19], v[16:17], off offset:768
	v_addc_co_u32_e32 v29, vcc, 0, v77, vcc
	v_add_co_u32_e32 v32, vcc, 0x318c0000, v76
	s_nop 1
	v_addc_co_u32_e32 v33, vcc, 0, v77, vcc
	v_add_co_u32_e32 v44, vcc, 0x1600000, v74
	global_load_dwordx4 v[28:31], v[28:29], off offset:768
	s_nop 0
	global_load_dwordx4 v[32:35], v[32:33], off offset:768
	v_addc_co_u32_e32 v45, vcc, 0, v75, vcc
	v_add_co_u32_e32 v48, vcc, 0x1640000, v74
	s_nop 1
	v_addc_co_u32_e32 v49, vcc, 0, v75, vcc
	global_load_dwordx4 v[44:47], v[44:45], off offset:768
	s_nop 0
	global_load_dwordx4 v[48:51], v[48:49], off offset:768
.LBB0_2634:
	s_andn2_b64 vcc, exec, s[6:7]
	ds_read_b128 v[90:93], v85 offset:52224
	ds_read_b128 v[94:97], v84 offset:52224
	ds_read_b128 v[98:101], v84 offset:56576
	ds_read_b128 v[102:105], v84 offset:60928
	ds_read_b128 v[106:109], v84 offset:65280
	ds_read_b128 v[110:113], v85 offset:52288
	ds_read_b128 v[114:117], v84 offset:52288
	s_waitcnt lgkmcnt(5)
	v_mfma_f32_16x16x32_bf16 v[52:55], v[94:97], v[90:93], v[52:55]
	ds_read_b128 v[94:97], v84 offset:56640
	s_waitcnt lgkmcnt(5)
	v_mfma_f32_16x16x32_bf16 v[56:59], v[98:101], v[90:93], v[56:59]
	ds_read_b128 v[98:101], v84 offset:60992
	s_waitcnt lgkmcnt(5)
	v_mfma_f32_16x16x32_bf16 v[60:63], v[102:105], v[90:93], v[60:63]
	ds_read_b128 v[102:105], v84 offset:65344
	s_waitcnt lgkmcnt(5)
	v_mfma_f32_16x16x32_bf16 v[64:67], v[106:109], v[90:93], v[64:67]
	ds_read_b128 v[90:93], v85 offset:52352
	ds_read_b128 v[106:109], v84 offset:52352
	s_waitcnt lgkmcnt(5)
	v_mfma_f32_16x16x32_bf16 v[52:55], v[114:117], v[110:113], v[52:55]
	ds_read_b128 v[114:117], v84 offset:56704
	s_waitcnt lgkmcnt(5)
	v_mfma_f32_16x16x32_bf16 v[56:59], v[94:97], v[110:113], v[56:59]
	ds_read_b128 v[94:97], v84 offset:61056
	s_waitcnt lgkmcnt(5)
	v_mfma_f32_16x16x32_bf16 v[60:63], v[98:101], v[110:113], v[60:63]
	ds_read_b128 v[98:101], v84 offset:65408
	s_waitcnt lgkmcnt(5)
	v_mfma_f32_16x16x32_bf16 v[64:67], v[102:105], v[110:113], v[64:67]
	ds_read_b128 v[102:105], v85 offset:52416
	ds_read_b128 v[110:113], v84 offset:52416
	s_waitcnt lgkmcnt(5)
	v_mfma_f32_16x16x32_bf16 v[52:55], v[106:109], v[90:93], v[52:55]
	ds_read_b128 v[106:109], v84 offset:56768
	s_waitcnt lgkmcnt(5)
	v_mfma_f32_16x16x32_bf16 v[56:59], v[114:117], v[90:93], v[56:59]
	ds_read_b128 v[114:117], v84 offset:61120
	s_waitcnt lgkmcnt(5)
	v_mfma_f32_16x16x32_bf16 v[60:63], v[94:97], v[90:93], v[60:63]
	ds_read_b128 v[94:97], v84 offset:65472
	s_waitcnt lgkmcnt(5)
	v_mfma_f32_16x16x32_bf16 v[74:77], v[98:101], v[90:93], v[64:67]
	s_waitcnt lgkmcnt(3)
	v_mfma_f32_16x16x32_bf16 v[52:55], v[110:113], v[102:105], v[52:55]
	s_waitcnt lgkmcnt(2)
	v_mfma_f32_16x16x32_bf16 v[64:67], v[106:109], v[102:105], v[56:59]
	s_waitcnt lgkmcnt(1)
	v_mfma_f32_16x16x32_bf16 v[60:63], v[114:117], v[102:105], v[60:63]
	s_waitcnt lgkmcnt(0)
	v_mfma_f32_16x16x32_bf16 v[56:59], v[94:97], v[102:105], v[74:77]
	s_waitcnt lgkmcnt(0)
	s_cbranch_vccnz .LBB0_2629
	ds_write_b128 v80, v[4:7]
	ds_write_b128 v80, v[8:11] offset:8704
	ds_write_b128 v80, v[20:23] offset:17408
	ds_write_b128 v80, v[24:27] offset:26112
	ds_write_b128 v80, v[36:39] offset:34816
	ds_write_b128 v80, v[40:43] offset:43520
	s_branch .LBB0_2629

.LBB0_2668:
	v_add_u32_e32 v94, 0, v79
	s_cmp_gt_u32 s10, 28
	ds_read_b128 v[96:99], v85
	ds_read_b128 v[100:103], v94 offset:34816
	ds_read_b128 v[104:107], v94 offset:39168
	ds_read_b128 v[108:111], v94 offset:43520
	ds_read_b128 v[112:115], v94 offset:47872
	ds_read_b128 v[116:119], v85 offset:64
	ds_read_b128 v[120:123], v94 offset:34880
	s_waitcnt lgkmcnt(5)
	v_mfma_f32_16x16x32_bf16 v[52:55], v[100:103], v[96:99], v[52:55]
	ds_read_b128 v[100:103], v94 offset:39232
	s_waitcnt lgkmcnt(5)
	v_mfma_f32_16x16x32_bf16 v[64:67], v[104:107], v[96:99], v[64:67]
	ds_read_b128 v[104:107], v94 offset:43584
	s_waitcnt lgkmcnt(5)
	v_mfma_f32_16x16x32_bf16 v[60:63], v[108:111], v[96:99], v[60:63]
	ds_read_b128 v[108:111], v94 offset:47936
	s_waitcnt lgkmcnt(5)
	v_mfma_f32_16x16x32_bf16 v[56:59], v[112:115], v[96:99], v[56:59]
	ds_read_b128 v[96:99], v85 offset:128
	ds_read_b128 v[112:115], v94 offset:34944
	s_waitcnt lgkmcnt(5)
	v_mfma_f32_16x16x32_bf16 v[52:55], v[120:123], v[116:119], v[52:55]
	ds_read_b128 v[120:123], v94 offset:39296
	s_waitcnt lgkmcnt(5)
	v_mfma_f32_16x16x32_bf16 v[64:67], v[100:103], v[116:119], v[64:67]
	ds_read_b128 v[100:103], v94 offset:43648
	s_waitcnt lgkmcnt(5)
	v_mfma_f32_16x16x32_bf16 v[60:63], v[104:107], v[116:119], v[60:63]
	ds_read_b128 v[104:107], v94 offset:48000
	s_waitcnt lgkmcnt(5)
	v_mfma_f32_16x16x32_bf16 v[56:59], v[108:111], v[116:119], v[56:59]
	ds_read_b128 v[90:93], v85 offset:192
	ds_read_b128 v[108:111], v94 offset:35008
	s_waitcnt lgkmcnt(5)
	v_mfma_f32_16x16x32_bf16 v[52:55], v[112:115], v[96:99], v[52:55]
	ds_read_b128 v[112:115], v94 offset:39360
	s_waitcnt lgkmcnt(5)
	v_mfma_f32_16x16x32_bf16 v[64:67], v[120:123], v[96:99], v[64:67]
	ds_read_b128 v[116:119], v94 offset:43712
	s_waitcnt lgkmcnt(5)
	v_mfma_f32_16x16x32_bf16 v[60:63], v[100:103], v[96:99], v[60:63]
	s_waitcnt lgkmcnt(4)
	v_mfma_f32_16x16x32_bf16 v[86:89], v[104:107], v[96:99], v[56:59]
	s_waitcnt lgkmcnt(2)
	v_mfma_f32_16x16x32_bf16 v[52:55], v[108:111], v[90:93], v[52:55]
	s_waitcnt lgkmcnt(1)
	v_mfma_f32_16x16x32_bf16 v[56:59], v[112:115], v[90:93], v[64:67]
	s_waitcnt lgkmcnt(0)
	v_mfma_f32_16x16x32_bf16 v[60:63], v[116:119], v[90:93], v[60:63]
	s_waitcnt lgkmcnt(0)
	ds_read_b128 v[64:67], v94 offset:48064
	s_waitcnt vmcnt(5)
	ds_write_b128 v80, v[12:15] offset:52224
	s_waitcnt vmcnt(4)
	ds_write_b128 v80, v[16:19] offset:60928
	s_waitcnt vmcnt(3)
	ds_write_b128 v81, v[28:31] offset:17408
	s_waitcnt vmcnt(2)
	ds_write_b128 v81, v[32:35] offset:26112
	s_waitcnt vmcnt(1)
	ds_write_b128 v82, v[44:47]
	s_waitcnt vmcnt(0)
	ds_write_b128 v83, v[48:51]
	s_waitcnt lgkmcnt(0)
	s_waitcnt lgkmcnt(6)
	v_mfma_f32_16x16x32_bf16 v[64:67], v[64:67], v[90:93], v[86:89]
	s_barrier
	s_cbranch_scc1 .LBB0_2670
	v_add_co_u32_e32 v12, vcc, 0x31800000, v76
	s_nop 1
	v_addc_co_u32_e32 v13, vcc, 0, v77, vcc
	v_add_co_u32_e32 v16, vcc, 0x31840000, v76
	s_nop 1
	v_addc_co_u32_e32 v17, vcc, 0, v77, vcc
	v_add_co_u32_e32 v28, vcc, 0x31880000, v76
	global_load_dwordx4 v[12:15], v[12:13], off offset:768
	s_nop 0
	global_load_dwordx4 v[16:19], v[16:17], off offset:768
	v_addc_co_u32_e32 v29, vcc, 0, v77, vcc
	v_add_co_u32_e32 v32, vcc, 0x318c0000, v76
	s_nop 1
	v_addc_co_u32_e32 v33, vcc, 0, v77, vcc
	v_add_co_u32_e32 v44, vcc, 0x1600000, v74
	global_load_dwordx4 v[28:31], v[28:29], off offset:768
	s_nop 0
	global_load_dwordx4 v[32:35], v[32:33], off offset:768
	v_addc_co_u32_e32 v45, vcc, 0, v75, vcc
	v_add_co_u32_e32 v48, vcc, 0x1640000, v74
	s_nop 1
	v_addc_co_u32_e32 v49, vcc, 0, v75, vcc
	global_load_dwordx4 v[44:47], v[44:45], off offset:768
	s_nop 0
	global_load_dwordx4 v[48:51], v[48:49], off offset:768
